# P3 state scan hand-written: 16 B per lane (waves 0-3), DEC staged in LDS by LDS-DMA, saddr addressing, counted waits; plus P8 epilogue vmcnt(0)->vmcnt(4); on top of KVT dwordx4 + P1 peel
# speedup vs baseline: 1.0135x; 1.0031x over previous
.LBB0_416:
	v_readlane_b32 s4, v252, 6
	v_readlane_b32 s5, v252, 7
	s_cmp_le_i32 s4, s2
	s_cselect_b64 s[4:5], -1, 0
	s_and_b64 s[0:1], s[4:5], s[0:1]
	s_andn2_b64 vcc, exec, s[0:1]
	s_cbranch_vccnz .LBB0_428
	v_readlane_b32 s2, v254, 20
	v_readlane_b32 s5, v252, 8
	v_readlane_b32 s6, v252, 11
	v_mov_b32_e32 v0, s2
	s_waitcnt vmcnt(19)
	ds_read_b64 v[2:3], v0
	v_mov_b32_e32 v0, v1
	v_readlane_b32 s7, v252, 12
	v_mbcnt_lo_u32_b32 v0, -1, v0
	v_mbcnt_hi_u32_b32 v110, -1, v0
	s_waitcnt lgkmcnt(0)
	v_readfirstlane_b32 s4, v2
	v_readfirstlane_b32 s2, v3
	v_add_u32_e32 v2, s5, v110
	v_ashrrev_i32_e32 v3, 31, v2
	s_waitcnt vmcnt(8)
	v_lshl_add_u64 v[66:67], s[6:7], 0, v[2:3]
	s_mov_b64 s[6:7], 0x20000
	v_cmp_gt_u64_e32 vcc, s[6:7], v[66:67]
	s_and_saveexec_b64 s[10:11], vcc
	s_cbranch_execz .LBB0_424
	v_readlane_b32 s12, v252, 13
	v_readlane_b32 s13, v252, 14
	s_cmp_lg_u32 s12, 0x20000
	s_cbranch_scc1 .Lscan16_orig
	s_cmp_lg_u32 s13, 0
	s_cbranch_scc1 .Lscan16_orig
	s_waitcnt vmcnt(0) lgkmcnt(0)
	v_readlane_b32 s6, v252, 11
	v_readlane_b32 s5, v252, 8
	s_lshr_b32 s20, s6, 15
	s_lshl_b32 s20, s20, 10
	s_add_u32 s14, s4, 0x4ff00000
	s_addc_u32 s15, s2, 0
	s_add_u32 s14, s14, s20
	s_addc_u32 s15, s15, 0
	v_lshlrev_b32_e32 v0, 4, v110
	s_lshl_b32 s21, s5, 6
	s_lshl_b32 s7, s5, 4
	s_add_u32 s12, s14, s21
	s_addc_u32 s13, s15, 0
	s_mov_b32 m0, s7
	s_nop 0
	global_load_lds_dwordx4 v0, s[12:13]
	s_add_i32 s21, s21, 0x8000
	s_add_i32 s7, s7, 0x2000
	s_add_u32 s12, s14, s21
	s_addc_u32 s13, s15, 0
	s_mov_b32 m0, s7
	s_nop 0
	global_load_lds_dwordx4 v0, s[12:13]
	s_add_i32 s21, s21, 0x8000
	s_add_i32 s7, s7, 0x2000
	s_add_u32 s12, s14, s21
	s_addc_u32 s13, s15, 0
	s_mov_b32 m0, s7
	s_nop 0
	global_load_lds_dwordx4 v0, s[12:13]
	s_add_i32 s21, s21, 0x8000
	s_add_i32 s7, s7, 0x2000
	s_add_u32 s12, s14, s21
	s_addc_u32 s13, s15, 0
	s_mov_b32 m0, s7
	s_nop 0
	global_load_lds_dwordx4 v0, s[12:13]
	s_add_i32 s21, s21, 0x8000
	s_add_i32 s7, s7, 0x2000
	s_add_u32 s12, s14, s21
	s_addc_u32 s13, s15, 0
	s_mov_b32 m0, s7
	s_nop 0
	global_load_lds_dwordx4 v0, s[12:13]
	s_add_i32 s21, s21, 0x8000
	s_add_i32 s7, s7, 0x2000
	s_add_u32 s12, s14, s21
	s_addc_u32 s13, s15, 0
	s_mov_b32 m0, s7
	s_nop 0
	global_load_lds_dwordx4 v0, s[12:13]
	s_add_i32 s21, s21, 0x8000
	s_add_i32 s7, s7, 0x2000
	s_add_u32 s12, s14, s21
	s_addc_u32 s13, s15, 0
	s_mov_b32 m0, s7
	s_nop 0
	global_load_lds_dwordx4 v0, s[12:13]
	s_add_i32 s21, s21, 0x8000
	s_add_i32 s7, s7, 0x2000
	s_add_u32 s12, s14, s21
	s_addc_u32 s13, s15, 0
	s_mov_b32 m0, s7
	s_nop 0
	global_load_lds_dwordx4 v0, s[12:13]
	s_waitcnt vmcnt(0)
	s_barrier
	s_cmpk_gt_u32 s5, 0xff
	s_cbranch_scc1 .Lscan16_done
	s_lshr_b32 s20, s6, 1
	s_add_i32 s20, s20, s5
	v_add_u32_e32 v108, s20, v110
	v_lshlrev_b32_e32 v108, 4, v108
	v_and_b32_e32 v109, 31, v110
	v_lshlrev_b32_e32 v109, 5, v109
	s_add_u32 s12, s4, 0x50000000
	s_addc_u32 s13, s2, 0
	s_mov_b64 s[16:17], s[12:13]
	v_mov_b32_e32 v2, 0
	v_mov_b32_e32 v3, 0
	v_mov_b32_e32 v4, 0
	v_mov_b32_e32 v5, 0
	v_mov_b32_e32 v6, 0
	v_mov_b32_e32 v7, 0
	v_mov_b32_e32 v8, 0
	v_mov_b32_e32 v9, 0
	global_load_dwordx4 v[10:13], v108, s[12:13] nt
	s_add_u32 s12, s12, 0x100000
	s_addc_u32 s13, s13, 0
	global_load_dwordx4 v[14:17], v108, s[12:13] nt
	s_add_u32 s12, s12, 0x100000
	s_addc_u32 s13, s13, 0
	global_load_dwordx4 v[18:21], v108, s[12:13] nt
	s_add_u32 s12, s12, 0x100000
	s_addc_u32 s13, s13, 0
	global_load_dwordx4 v[22:25], v108, s[12:13] nt
	s_add_u32 s12, s12, 0x100000
	s_addc_u32 s13, s13, 0
	global_load_dwordx4 v[26:29], v108, s[12:13] nt
	s_add_u32 s12, s12, 0x100000
	s_addc_u32 s13, s13, 0
	global_load_dwordx4 v[30:33], v108, s[12:13] nt
	s_add_u32 s12, s12, 0x100000
	s_addc_u32 s13, s13, 0
	global_load_dwordx4 v[34:37], v108, s[12:13] nt
	s_add_u32 s12, s12, 0x100000
	s_addc_u32 s13, s13, 0
	global_load_dwordx4 v[38:41], v108, s[12:13] nt
	s_add_u32 s12, s12, 0x100000
	s_addc_u32 s13, s13, 0
	ds_read_b128 v[76:79], v109 offset:0
	ds_read_b128 v[80:83], v109 offset:16
	global_load_dwordx4 v[42:45], v108, s[12:13] nt
	s_add_u32 s12, s12, 0x100000
	s_addc_u32 s13, s13, 0
	global_load_dwordx4 v[46:49], v108, s[12:13] nt
	s_add_u32 s12, s12, 0x100000
	s_addc_u32 s13, s13, 0
	global_load_dwordx4 v[50:53], v108, s[12:13] nt
	s_add_u32 s12, s12, 0x100000
	s_addc_u32 s13, s13, 0
	global_load_dwordx4 v[54:57], v108, s[12:13] nt
	s_add_u32 s12, s12, 0x100000
	s_addc_u32 s13, s13, 0
	global_load_dwordx4 v[58:61], v108, s[12:13] nt
	s_add_u32 s12, s12, 0x100000
	s_addc_u32 s13, s13, 0
	global_load_dwordx4 v[62:65], v108, s[12:13] nt
	s_add_u32 s12, s12, 0x100000
	s_addc_u32 s13, s13, 0
	global_load_dwordx4 v[68:71], v108, s[12:13] nt
	s_add_u32 s12, s12, 0x100000
	s_addc_u32 s13, s13, 0
	global_load_dwordx4 v[72:75], v108, s[12:13] nt
	s_add_u32 s12, s12, 0x100000
	s_addc_u32 s13, s13, 0
	ds_read_b128 v[84:87], v109 offset:1024
	ds_read_b128 v[88:91], v109 offset:1040
	v_cvt_pk_bf16_f32 v92, v2, v3
	v_cvt_pk_bf16_f32 v93, v4, v5
	v_cvt_pk_bf16_f32 v94, v6, v7
	v_cvt_pk_bf16_f32 v95, v8, v9
	s_waitcnt vmcnt(15)
	global_store_dwordx4 v108, v[92:95], s[16:17]
	s_add_u32 s16, s16, 0x100000
	s_addc_u32 s17, s17, 0
	v_lshlrev_b32_e32 v100, 16, v10
	v_and_b32_e32 v101, 0xffff0000, v10
	v_lshlrev_b32_e32 v102, 16, v11
	v_and_b32_e32 v103, 0xffff0000, v11
	v_lshlrev_b32_e32 v104, 16, v12
	v_and_b32_e32 v105, 0xffff0000, v12
	v_lshlrev_b32_e32 v106, 16, v13
	v_and_b32_e32 v107, 0xffff0000, v13
	s_waitcnt lgkmcnt(2)
	v_pk_fma_f32 v[2:3], v[2:3], v[76:77], v[100:101]
	v_pk_fma_f32 v[4:5], v[4:5], v[78:79], v[102:103]
	v_pk_fma_f32 v[6:7], v[6:7], v[80:81], v[104:105]
	v_pk_fma_f32 v[8:9], v[8:9], v[82:83], v[106:107]
	ds_read_b128 v[76:79], v109 offset:2048
	ds_read_b128 v[80:83], v109 offset:2064
	v_cvt_pk_bf16_f32 v96, v2, v3
	v_cvt_pk_bf16_f32 v97, v4, v5
	v_cvt_pk_bf16_f32 v98, v6, v7
	v_cvt_pk_bf16_f32 v99, v8, v9
	s_waitcnt vmcnt(15)
	global_store_dwordx4 v108, v[96:99], s[16:17]
	s_add_u32 s16, s16, 0x100000
	s_addc_u32 s17, s17, 0
	v_lshlrev_b32_e32 v100, 16, v14
	v_and_b32_e32 v101, 0xffff0000, v14
	v_lshlrev_b32_e32 v102, 16, v15
	v_and_b32_e32 v103, 0xffff0000, v15
	v_lshlrev_b32_e32 v104, 16, v16
	v_and_b32_e32 v105, 0xffff0000, v16
	v_lshlrev_b32_e32 v106, 16, v17
	v_and_b32_e32 v107, 0xffff0000, v17
	s_waitcnt lgkmcnt(2)
	v_pk_fma_f32 v[2:3], v[2:3], v[84:85], v[100:101]
	v_pk_fma_f32 v[4:5], v[4:5], v[86:87], v[102:103]
	v_pk_fma_f32 v[6:7], v[6:7], v[88:89], v[104:105]
	v_pk_fma_f32 v[8:9], v[8:9], v[90:91], v[106:107]
	ds_read_b128 v[84:87], v109 offset:3072
	ds_read_b128 v[88:91], v109 offset:3088
	v_cvt_pk_bf16_f32 v92, v2, v3
	v_cvt_pk_bf16_f32 v93, v4, v5
	v_cvt_pk_bf16_f32 v94, v6, v7
	v_cvt_pk_bf16_f32 v95, v8, v9
	s_waitcnt vmcnt(15)
	global_store_dwordx4 v108, v[92:95], s[16:17]
	s_add_u32 s16, s16, 0x100000
	s_addc_u32 s17, s17, 0
	v_lshlrev_b32_e32 v100, 16, v18
	v_and_b32_e32 v101, 0xffff0000, v18
	v_lshlrev_b32_e32 v102, 16, v19
	v_and_b32_e32 v103, 0xffff0000, v19
	v_lshlrev_b32_e32 v104, 16, v20
	v_and_b32_e32 v105, 0xffff0000, v20
	v_lshlrev_b32_e32 v106, 16, v21
	v_and_b32_e32 v107, 0xffff0000, v21
	s_waitcnt lgkmcnt(2)
	v_pk_fma_f32 v[2:3], v[2:3], v[76:77], v[100:101]
	v_pk_fma_f32 v[4:5], v[4:5], v[78:79], v[102:103]
	v_pk_fma_f32 v[6:7], v[6:7], v[80:81], v[104:105]
	v_pk_fma_f32 v[8:9], v[8:9], v[82:83], v[106:107]
	ds_read_b128 v[76:79], v109 offset:4096
	ds_read_b128 v[80:83], v109 offset:4112
	v_cvt_pk_bf16_f32 v96, v2, v3
	v_cvt_pk_bf16_f32 v97, v4, v5
	v_cvt_pk_bf16_f32 v98, v6, v7
	v_cvt_pk_bf16_f32 v99, v8, v9
	s_waitcnt vmcnt(15)
	global_store_dwordx4 v108, v[96:99], s[16:17]
	s_add_u32 s16, s16, 0x100000
	s_addc_u32 s17, s17, 0
	v_lshlrev_b32_e32 v100, 16, v22
	v_and_b32_e32 v101, 0xffff0000, v22
	v_lshlrev_b32_e32 v102, 16, v23
	v_and_b32_e32 v103, 0xffff0000, v23
	v_lshlrev_b32_e32 v104, 16, v24
	v_and_b32_e32 v105, 0xffff0000, v24
	v_lshlrev_b32_e32 v106, 16, v25
	v_and_b32_e32 v107, 0xffff0000, v25
	s_waitcnt lgkmcnt(2)
	v_pk_fma_f32 v[2:3], v[2:3], v[84:85], v[100:101]
	v_pk_fma_f32 v[4:5], v[4:5], v[86:87], v[102:103]
	v_pk_fma_f32 v[6:7], v[6:7], v[88:89], v[104:105]
	v_pk_fma_f32 v[8:9], v[8:9], v[90:91], v[106:107]
	ds_read_b128 v[84:87], v109 offset:5120
	ds_read_b128 v[88:91], v109 offset:5136
	v_cvt_pk_bf16_f32 v92, v2, v3
	v_cvt_pk_bf16_f32 v93, v4, v5
	v_cvt_pk_bf16_f32 v94, v6, v7
	v_cvt_pk_bf16_f32 v95, v8, v9
	s_waitcnt vmcnt(15)
	global_store_dwordx4 v108, v[92:95], s[16:17]
	s_add_u32 s16, s16, 0x100000
	s_addc_u32 s17, s17, 0
	v_lshlrev_b32_e32 v100, 16, v26
	v_and_b32_e32 v101, 0xffff0000, v26
	v_lshlrev_b32_e32 v102, 16, v27
	v_and_b32_e32 v103, 0xffff0000, v27
	v_lshlrev_b32_e32 v104, 16, v28
	v_and_b32_e32 v105, 0xffff0000, v28
	v_lshlrev_b32_e32 v106, 16, v29
	v_and_b32_e32 v107, 0xffff0000, v29
	s_waitcnt lgkmcnt(2)
	v_pk_fma_f32 v[2:3], v[2:3], v[76:77], v[100:101]
	v_pk_fma_f32 v[4:5], v[4:5], v[78:79], v[102:103]
	v_pk_fma_f32 v[6:7], v[6:7], v[80:81], v[104:105]
	v_pk_fma_f32 v[8:9], v[8:9], v[82:83], v[106:107]
	ds_read_b128 v[76:79], v109 offset:6144
	ds_read_b128 v[80:83], v109 offset:6160
	v_cvt_pk_bf16_f32 v96, v2, v3
	v_cvt_pk_bf16_f32 v97, v4, v5
	v_cvt_pk_bf16_f32 v98, v6, v7
	v_cvt_pk_bf16_f32 v99, v8, v9
	s_waitcnt vmcnt(15)
	global_store_dwordx4 v108, v[96:99], s[16:17]
	s_add_u32 s16, s16, 0x100000
	s_addc_u32 s17, s17, 0
	v_lshlrev_b32_e32 v100, 16, v30
	v_and_b32_e32 v101, 0xffff0000, v30
	v_lshlrev_b32_e32 v102, 16, v31
	v_and_b32_e32 v103, 0xffff0000, v31
	v_lshlrev_b32_e32 v104, 16, v32
	v_and_b32_e32 v105, 0xffff0000, v32
	v_lshlrev_b32_e32 v106, 16, v33
	v_and_b32_e32 v107, 0xffff0000, v33
	s_waitcnt lgkmcnt(2)
	v_pk_fma_f32 v[2:3], v[2:3], v[84:85], v[100:101]
	v_pk_fma_f32 v[4:5], v[4:5], v[86:87], v[102:103]
	v_pk_fma_f32 v[6:7], v[6:7], v[88:89], v[104:105]
	v_pk_fma_f32 v[8:9], v[8:9], v[90:91], v[106:107]
	ds_read_b128 v[84:87], v109 offset:7168
	ds_read_b128 v[88:91], v109 offset:7184
	v_cvt_pk_bf16_f32 v92, v2, v3
	v_cvt_pk_bf16_f32 v93, v4, v5
	v_cvt_pk_bf16_f32 v94, v6, v7
	v_cvt_pk_bf16_f32 v95, v8, v9
	s_waitcnt vmcnt(15)
	global_store_dwordx4 v108, v[92:95], s[16:17]
	s_add_u32 s16, s16, 0x100000
	s_addc_u32 s17, s17, 0
	v_lshlrev_b32_e32 v100, 16, v34
	v_and_b32_e32 v101, 0xffff0000, v34
	v_lshlrev_b32_e32 v102, 16, v35
	v_and_b32_e32 v103, 0xffff0000, v35
	v_lshlrev_b32_e32 v104, 16, v36
	v_and_b32_e32 v105, 0xffff0000, v36
	v_lshlrev_b32_e32 v106, 16, v37
	v_and_b32_e32 v107, 0xffff0000, v37
	s_waitcnt lgkmcnt(2)
	v_pk_fma_f32 v[2:3], v[2:3], v[76:77], v[100:101]
	v_pk_fma_f32 v[4:5], v[4:5], v[78:79], v[102:103]
	v_pk_fma_f32 v[6:7], v[6:7], v[80:81], v[104:105]
	v_pk_fma_f32 v[8:9], v[8:9], v[82:83], v[106:107]
	ds_read_b128 v[76:79], v109 offset:8192
	ds_read_b128 v[80:83], v109 offset:8208
	v_cvt_pk_bf16_f32 v96, v2, v3
	v_cvt_pk_bf16_f32 v97, v4, v5
	v_cvt_pk_bf16_f32 v98, v6, v7
	v_cvt_pk_bf16_f32 v99, v8, v9
	s_waitcnt vmcnt(15)
	global_store_dwordx4 v108, v[96:99], s[16:17]
	s_add_u32 s16, s16, 0x100000
	s_addc_u32 s17, s17, 0
	v_lshlrev_b32_e32 v100, 16, v38
	v_and_b32_e32 v101, 0xffff0000, v38
	v_lshlrev_b32_e32 v102, 16, v39
	v_and_b32_e32 v103, 0xffff0000, v39
	v_lshlrev_b32_e32 v104, 16, v40
	v_and_b32_e32 v105, 0xffff0000, v40
	v_lshlrev_b32_e32 v106, 16, v41
	v_and_b32_e32 v107, 0xffff0000, v41
	s_waitcnt lgkmcnt(2)
	v_pk_fma_f32 v[2:3], v[2:3], v[84:85], v[100:101]
	v_pk_fma_f32 v[4:5], v[4:5], v[86:87], v[102:103]
	v_pk_fma_f32 v[6:7], v[6:7], v[88:89], v[104:105]
	v_pk_fma_f32 v[8:9], v[8:9], v[90:91], v[106:107]
	global_load_dwordx4 v[10:13], v108, s[12:13] nt
	s_add_u32 s12, s12, 0x100000
	s_addc_u32 s13, s13, 0
	global_load_dwordx4 v[14:17], v108, s[12:13] nt
	s_add_u32 s12, s12, 0x100000
	s_addc_u32 s13, s13, 0
	global_load_dwordx4 v[18:21], v108, s[12:13] nt
	s_add_u32 s12, s12, 0x100000
	s_addc_u32 s13, s13, 0
	global_load_dwordx4 v[22:25], v108, s[12:13] nt
	s_add_u32 s12, s12, 0x100000
	s_addc_u32 s13, s13, 0
	global_load_dwordx4 v[26:29], v108, s[12:13] nt
	s_add_u32 s12, s12, 0x100000
	s_addc_u32 s13, s13, 0
	global_load_dwordx4 v[30:33], v108, s[12:13] nt
	s_add_u32 s12, s12, 0x100000
	s_addc_u32 s13, s13, 0
	global_load_dwordx4 v[34:37], v108, s[12:13] nt
	s_add_u32 s12, s12, 0x100000
	s_addc_u32 s13, s13, 0
	global_load_dwordx4 v[38:41], v108, s[12:13] nt
	s_add_u32 s12, s12, 0x100000
	s_addc_u32 s13, s13, 0
	ds_read_b128 v[84:87], v109 offset:9216
	ds_read_b128 v[88:91], v109 offset:9232
	v_cvt_pk_bf16_f32 v92, v2, v3
	v_cvt_pk_bf16_f32 v93, v4, v5
	v_cvt_pk_bf16_f32 v94, v6, v7
	v_cvt_pk_bf16_f32 v95, v8, v9
	s_waitcnt vmcnt(23)
	global_store_dwordx4 v108, v[92:95], s[16:17]
	s_add_u32 s16, s16, 0x100000
	s_addc_u32 s17, s17, 0
	v_lshlrev_b32_e32 v100, 16, v42
	v_and_b32_e32 v101, 0xffff0000, v42
	v_lshlrev_b32_e32 v102, 16, v43
	v_and_b32_e32 v103, 0xffff0000, v43
	v_lshlrev_b32_e32 v104, 16, v44
	v_and_b32_e32 v105, 0xffff0000, v44
	v_lshlrev_b32_e32 v106, 16, v45
	v_and_b32_e32 v107, 0xffff0000, v45
	s_waitcnt lgkmcnt(2)
	v_pk_fma_f32 v[2:3], v[2:3], v[76:77], v[100:101]
	v_pk_fma_f32 v[4:5], v[4:5], v[78:79], v[102:103]
	v_pk_fma_f32 v[6:7], v[6:7], v[80:81], v[104:105]
	v_pk_fma_f32 v[8:9], v[8:9], v[82:83], v[106:107]
	ds_read_b128 v[76:79], v109 offset:10240
	ds_read_b128 v[80:83], v109 offset:10256
	v_cvt_pk_bf16_f32 v96, v2, v3
	v_cvt_pk_bf16_f32 v97, v4, v5
	v_cvt_pk_bf16_f32 v98, v6, v7
	v_cvt_pk_bf16_f32 v99, v8, v9
	s_waitcnt vmcnt(23)
	global_store_dwordx4 v108, v[96:99], s[16:17]
	s_add_u32 s16, s16, 0x100000
	s_addc_u32 s17, s17, 0
	v_lshlrev_b32_e32 v100, 16, v46
	v_and_b32_e32 v101, 0xffff0000, v46
	v_lshlrev_b32_e32 v102, 16, v47
	v_and_b32_e32 v103, 0xffff0000, v47
	v_lshlrev_b32_e32 v104, 16, v48
	v_and_b32_e32 v105, 0xffff0000, v48
	v_lshlrev_b32_e32 v106, 16, v49
	v_and_b32_e32 v107, 0xffff0000, v49
	s_waitcnt lgkmcnt(2)
	v_pk_fma_f32 v[2:3], v[2:3], v[84:85], v[100:101]
	v_pk_fma_f32 v[4:5], v[4:5], v[86:87], v[102:103]
	v_pk_fma_f32 v[6:7], v[6:7], v[88:89], v[104:105]
	v_pk_fma_f32 v[8:9], v[8:9], v[90:91], v[106:107]
	ds_read_b128 v[84:87], v109 offset:11264
	ds_read_b128 v[88:91], v109 offset:11280
	v_cvt_pk_bf16_f32 v92, v2, v3
	v_cvt_pk_bf16_f32 v93, v4, v5
	v_cvt_pk_bf16_f32 v94, v6, v7
	v_cvt_pk_bf16_f32 v95, v8, v9
	s_waitcnt vmcnt(23)
	global_store_dwordx4 v108, v[92:95], s[16:17]
	s_add_u32 s16, s16, 0x100000
	s_addc_u32 s17, s17, 0
	v_lshlrev_b32_e32 v100, 16, v50
	v_and_b32_e32 v101, 0xffff0000, v50
	v_lshlrev_b32_e32 v102, 16, v51
	v_and_b32_e32 v103, 0xffff0000, v51
	v_lshlrev_b32_e32 v104, 16, v52
	v_and_b32_e32 v105, 0xffff0000, v52
	v_lshlrev_b32_e32 v106, 16, v53
	v_and_b32_e32 v107, 0xffff0000, v53
	s_waitcnt lgkmcnt(2)
	v_pk_fma_f32 v[2:3], v[2:3], v[76:77], v[100:101]
	v_pk_fma_f32 v[4:5], v[4:5], v[78:79], v[102:103]
	v_pk_fma_f32 v[6:7], v[6:7], v[80:81], v[104:105]
	v_pk_fma_f32 v[8:9], v[8:9], v[82:83], v[106:107]
	ds_read_b128 v[76:79], v109 offset:12288
	ds_read_b128 v[80:83], v109 offset:12304
	v_cvt_pk_bf16_f32 v96, v2, v3
	v_cvt_pk_bf16_f32 v97, v4, v5
	v_cvt_pk_bf16_f32 v98, v6, v7
	v_cvt_pk_bf16_f32 v99, v8, v9
	s_waitcnt vmcnt(23)
	global_store_dwordx4 v108, v[96:99], s[16:17]
	s_add_u32 s16, s16, 0x100000
	s_addc_u32 s17, s17, 0
	v_lshlrev_b32_e32 v100, 16, v54
	v_and_b32_e32 v101, 0xffff0000, v54
	v_lshlrev_b32_e32 v102, 16, v55
	v_and_b32_e32 v103, 0xffff0000, v55
	v_lshlrev_b32_e32 v104, 16, v56
	v_and_b32_e32 v105, 0xffff0000, v56
	v_lshlrev_b32_e32 v106, 16, v57
	v_and_b32_e32 v107, 0xffff0000, v57
	s_waitcnt lgkmcnt(2)
	v_pk_fma_f32 v[2:3], v[2:3], v[84:85], v[100:101]
	v_pk_fma_f32 v[4:5], v[4:5], v[86:87], v[102:103]
	v_pk_fma_f32 v[6:7], v[6:7], v[88:89], v[104:105]
	v_pk_fma_f32 v[8:9], v[8:9], v[90:91], v[106:107]
	ds_read_b128 v[84:87], v109 offset:13312
	ds_read_b128 v[88:91], v109 offset:13328
	v_cvt_pk_bf16_f32 v92, v2, v3
	v_cvt_pk_bf16_f32 v93, v4, v5
	v_cvt_pk_bf16_f32 v94, v6, v7
	v_cvt_pk_bf16_f32 v95, v8, v9
	s_waitcnt vmcnt(23)
	global_store_dwordx4 v108, v[92:95], s[16:17]
	s_add_u32 s16, s16, 0x100000
	s_addc_u32 s17, s17, 0
	v_lshlrev_b32_e32 v100, 16, v58
	v_and_b32_e32 v101, 0xffff0000, v58
	v_lshlrev_b32_e32 v102, 16, v59
	v_and_b32_e32 v103, 0xffff0000, v59
	v_lshlrev_b32_e32 v104, 16, v60
	v_and_b32_e32 v105, 0xffff0000, v60
	v_lshlrev_b32_e32 v106, 16, v61
	v_and_b32_e32 v107, 0xffff0000, v61
	s_waitcnt lgkmcnt(2)
	v_pk_fma_f32 v[2:3], v[2:3], v[76:77], v[100:101]
	v_pk_fma_f32 v[4:5], v[4:5], v[78:79], v[102:103]
	v_pk_fma_f32 v[6:7], v[6:7], v[80:81], v[104:105]
	v_pk_fma_f32 v[8:9], v[8:9], v[82:83], v[106:107]
	ds_read_b128 v[76:79], v109 offset:14336
	ds_read_b128 v[80:83], v109 offset:14352
	v_cvt_pk_bf16_f32 v96, v2, v3
	v_cvt_pk_bf16_f32 v97, v4, v5
	v_cvt_pk_bf16_f32 v98, v6, v7
	v_cvt_pk_bf16_f32 v99, v8, v9
	s_waitcnt vmcnt(23)
	global_store_dwordx4 v108, v[96:99], s[16:17]
	s_add_u32 s16, s16, 0x100000
	s_addc_u32 s17, s17, 0
	v_lshlrev_b32_e32 v100, 16, v62
	v_and_b32_e32 v101, 0xffff0000, v62
	v_lshlrev_b32_e32 v102, 16, v63
	v_and_b32_e32 v103, 0xffff0000, v63
	v_lshlrev_b32_e32 v104, 16, v64
	v_and_b32_e32 v105, 0xffff0000, v64
	v_lshlrev_b32_e32 v106, 16, v65
	v_and_b32_e32 v107, 0xffff0000, v65
	s_waitcnt lgkmcnt(2)
	v_pk_fma_f32 v[2:3], v[2:3], v[84:85], v[100:101]
	v_pk_fma_f32 v[4:5], v[4:5], v[86:87], v[102:103]
	v_pk_fma_f32 v[6:7], v[6:7], v[88:89], v[104:105]
	v_pk_fma_f32 v[8:9], v[8:9], v[90:91], v[106:107]
	ds_read_b128 v[84:87], v109 offset:15360
	ds_read_b128 v[88:91], v109 offset:15376
	v_cvt_pk_bf16_f32 v92, v2, v3
	v_cvt_pk_bf16_f32 v93, v4, v5
	v_cvt_pk_bf16_f32 v94, v6, v7
	v_cvt_pk_bf16_f32 v95, v8, v9
	s_waitcnt vmcnt(23)
	global_store_dwordx4 v108, v[92:95], s[16:17]
	s_add_u32 s16, s16, 0x100000
	s_addc_u32 s17, s17, 0
	v_lshlrev_b32_e32 v100, 16, v68
	v_and_b32_e32 v101, 0xffff0000, v68
	v_lshlrev_b32_e32 v102, 16, v69
	v_and_b32_e32 v103, 0xffff0000, v69
	v_lshlrev_b32_e32 v104, 16, v70
	v_and_b32_e32 v105, 0xffff0000, v70
	v_lshlrev_b32_e32 v106, 16, v71
	v_and_b32_e32 v107, 0xffff0000, v71
	s_waitcnt lgkmcnt(2)
	v_pk_fma_f32 v[2:3], v[2:3], v[76:77], v[100:101]
	v_pk_fma_f32 v[4:5], v[4:5], v[78:79], v[102:103]
	v_pk_fma_f32 v[6:7], v[6:7], v[80:81], v[104:105]
	v_pk_fma_f32 v[8:9], v[8:9], v[82:83], v[106:107]
	ds_read_b128 v[76:79], v109 offset:16384
	ds_read_b128 v[80:83], v109 offset:16400
	v_cvt_pk_bf16_f32 v96, v2, v3
	v_cvt_pk_bf16_f32 v97, v4, v5
	v_cvt_pk_bf16_f32 v98, v6, v7
	v_cvt_pk_bf16_f32 v99, v8, v9
	s_waitcnt vmcnt(23)
	global_store_dwordx4 v108, v[96:99], s[16:17]
	s_add_u32 s16, s16, 0x100000
	s_addc_u32 s17, s17, 0
	v_lshlrev_b32_e32 v100, 16, v72
	v_and_b32_e32 v101, 0xffff0000, v72
	v_lshlrev_b32_e32 v102, 16, v73
	v_and_b32_e32 v103, 0xffff0000, v73
	v_lshlrev_b32_e32 v104, 16, v74
	v_and_b32_e32 v105, 0xffff0000, v74
	v_lshlrev_b32_e32 v106, 16, v75
	v_and_b32_e32 v107, 0xffff0000, v75
	s_waitcnt lgkmcnt(2)
	v_pk_fma_f32 v[2:3], v[2:3], v[84:85], v[100:101]
	v_pk_fma_f32 v[4:5], v[4:5], v[86:87], v[102:103]
	v_pk_fma_f32 v[6:7], v[6:7], v[88:89], v[104:105]
	v_pk_fma_f32 v[8:9], v[8:9], v[90:91], v[106:107]
	global_load_dwordx4 v[42:45], v108, s[12:13] nt
	s_add_u32 s12, s12, 0x100000
	s_addc_u32 s13, s13, 0
	global_load_dwordx4 v[46:49], v108, s[12:13] nt
	s_add_u32 s12, s12, 0x100000
	s_addc_u32 s13, s13, 0
	global_load_dwordx4 v[50:53], v108, s[12:13] nt
	s_add_u32 s12, s12, 0x100000
	s_addc_u32 s13, s13, 0
	global_load_dwordx4 v[54:57], v108, s[12:13] nt
	s_add_u32 s12, s12, 0x100000
	s_addc_u32 s13, s13, 0
	global_load_dwordx4 v[58:61], v108, s[12:13] nt
	s_add_u32 s12, s12, 0x100000
	s_addc_u32 s13, s13, 0
	global_load_dwordx4 v[62:65], v108, s[12:13] nt
	s_add_u32 s12, s12, 0x100000
	s_addc_u32 s13, s13, 0
	global_load_dwordx4 v[68:71], v108, s[12:13] nt
	s_add_u32 s12, s12, 0x100000
	s_addc_u32 s13, s13, 0
	global_load_dwordx4 v[72:75], v108, s[12:13] nt
	s_add_u32 s12, s12, 0x100000
	s_addc_u32 s13, s13, 0
	ds_read_b128 v[84:87], v109 offset:17408
	ds_read_b128 v[88:91], v109 offset:17424
	v_cvt_pk_bf16_f32 v92, v2, v3
	v_cvt_pk_bf16_f32 v93, v4, v5
	v_cvt_pk_bf16_f32 v94, v6, v7
	v_cvt_pk_bf16_f32 v95, v8, v9
	s_waitcnt vmcnt(23)
	global_store_dwordx4 v108, v[92:95], s[16:17]
	s_add_u32 s16, s16, 0x100000
	s_addc_u32 s17, s17, 0
	v_lshlrev_b32_e32 v100, 16, v10
	v_and_b32_e32 v101, 0xffff0000, v10
	v_lshlrev_b32_e32 v102, 16, v11
	v_and_b32_e32 v103, 0xffff0000, v11
	v_lshlrev_b32_e32 v104, 16, v12
	v_and_b32_e32 v105, 0xffff0000, v12
	v_lshlrev_b32_e32 v106, 16, v13
	v_and_b32_e32 v107, 0xffff0000, v13
	s_waitcnt lgkmcnt(2)
	v_pk_fma_f32 v[2:3], v[2:3], v[76:77], v[100:101]
	v_pk_fma_f32 v[4:5], v[4:5], v[78:79], v[102:103]
	v_pk_fma_f32 v[6:7], v[6:7], v[80:81], v[104:105]
	v_pk_fma_f32 v[8:9], v[8:9], v[82:83], v[106:107]
	ds_read_b128 v[76:79], v109 offset:18432
	ds_read_b128 v[80:83], v109 offset:18448
	v_cvt_pk_bf16_f32 v96, v2, v3
	v_cvt_pk_bf16_f32 v97, v4, v5
	v_cvt_pk_bf16_f32 v98, v6, v7
	v_cvt_pk_bf16_f32 v99, v8, v9
	s_waitcnt vmcnt(23)
	global_store_dwordx4 v108, v[96:99], s[16:17]
	s_add_u32 s16, s16, 0x100000
	s_addc_u32 s17, s17, 0
	v_lshlrev_b32_e32 v100, 16, v14
	v_and_b32_e32 v101, 0xffff0000, v14
	v_lshlrev_b32_e32 v102, 16, v15
	v_and_b32_e32 v103, 0xffff0000, v15
	v_lshlrev_b32_e32 v104, 16, v16
	v_and_b32_e32 v105, 0xffff0000, v16
	v_lshlrev_b32_e32 v106, 16, v17
	v_and_b32_e32 v107, 0xffff0000, v17
	s_waitcnt lgkmcnt(2)
	v_pk_fma_f32 v[2:3], v[2:3], v[84:85], v[100:101]
	v_pk_fma_f32 v[4:5], v[4:5], v[86:87], v[102:103]
	v_pk_fma_f32 v[6:7], v[6:7], v[88:89], v[104:105]
	v_pk_fma_f32 v[8:9], v[8:9], v[90:91], v[106:107]
	ds_read_b128 v[84:87], v109 offset:19456
	ds_read_b128 v[88:91], v109 offset:19472
	v_cvt_pk_bf16_f32 v92, v2, v3
	v_cvt_pk_bf16_f32 v93, v4, v5
	v_cvt_pk_bf16_f32 v94, v6, v7
	v_cvt_pk_bf16_f32 v95, v8, v9
	s_waitcnt vmcnt(23)
	global_store_dwordx4 v108, v[92:95], s[16:17]
	s_add_u32 s16, s16, 0x100000
	s_addc_u32 s17, s17, 0
	v_lshlrev_b32_e32 v100, 16, v18
	v_and_b32_e32 v101, 0xffff0000, v18
	v_lshlrev_b32_e32 v102, 16, v19
	v_and_b32_e32 v103, 0xffff0000, v19
	v_lshlrev_b32_e32 v104, 16, v20
	v_and_b32_e32 v105, 0xffff0000, v20
	v_lshlrev_b32_e32 v106, 16, v21
	v_and_b32_e32 v107, 0xffff0000, v21
	s_waitcnt lgkmcnt(2)
	v_pk_fma_f32 v[2:3], v[2:3], v[76:77], v[100:101]
	v_pk_fma_f32 v[4:5], v[4:5], v[78:79], v[102:103]
	v_pk_fma_f32 v[6:7], v[6:7], v[80:81], v[104:105]
	v_pk_fma_f32 v[8:9], v[8:9], v[82:83], v[106:107]
	ds_read_b128 v[76:79], v109 offset:20480
	ds_read_b128 v[80:83], v109 offset:20496
	v_cvt_pk_bf16_f32 v96, v2, v3
	v_cvt_pk_bf16_f32 v97, v4, v5
	v_cvt_pk_bf16_f32 v98, v6, v7
	v_cvt_pk_bf16_f32 v99, v8, v9
	s_waitcnt vmcnt(23)
	global_store_dwordx4 v108, v[96:99], s[16:17]
	s_add_u32 s16, s16, 0x100000
	s_addc_u32 s17, s17, 0
	v_lshlrev_b32_e32 v100, 16, v22
	v_and_b32_e32 v101, 0xffff0000, v22
	v_lshlrev_b32_e32 v102, 16, v23
	v_and_b32_e32 v103, 0xffff0000, v23
	v_lshlrev_b32_e32 v104, 16, v24
	v_and_b32_e32 v105, 0xffff0000, v24
	v_lshlrev_b32_e32 v106, 16, v25
	v_and_b32_e32 v107, 0xffff0000, v25
	s_waitcnt lgkmcnt(2)
	v_pk_fma_f32 v[2:3], v[2:3], v[84:85], v[100:101]
	v_pk_fma_f32 v[4:5], v[4:5], v[86:87], v[102:103]
	v_pk_fma_f32 v[6:7], v[6:7], v[88:89], v[104:105]
	v_pk_fma_f32 v[8:9], v[8:9], v[90:91], v[106:107]
	ds_read_b128 v[84:87], v109 offset:21504
	ds_read_b128 v[88:91], v109 offset:21520
	v_cvt_pk_bf16_f32 v92, v2, v3
	v_cvt_pk_bf16_f32 v93, v4, v5
	v_cvt_pk_bf16_f32 v94, v6, v7
	v_cvt_pk_bf16_f32 v95, v8, v9
	s_waitcnt vmcnt(23)
	global_store_dwordx4 v108, v[92:95], s[16:17]
	s_add_u32 s16, s16, 0x100000
	s_addc_u32 s17, s17, 0
	v_lshlrev_b32_e32 v100, 16, v26
	v_and_b32_e32 v101, 0xffff0000, v26
	v_lshlrev_b32_e32 v102, 16, v27
	v_and_b32_e32 v103, 0xffff0000, v27
	v_lshlrev_b32_e32 v104, 16, v28
	v_and_b32_e32 v105, 0xffff0000, v28
	v_lshlrev_b32_e32 v106, 16, v29
	v_and_b32_e32 v107, 0xffff0000, v29
	s_waitcnt lgkmcnt(2)
	v_pk_fma_f32 v[2:3], v[2:3], v[76:77], v[100:101]
	v_pk_fma_f32 v[4:5], v[4:5], v[78:79], v[102:103]
	v_pk_fma_f32 v[6:7], v[6:7], v[80:81], v[104:105]
	v_pk_fma_f32 v[8:9], v[8:9], v[82:83], v[106:107]
	ds_read_b128 v[76:79], v109 offset:22528
	ds_read_b128 v[80:83], v109 offset:22544
	v_cvt_pk_bf16_f32 v96, v2, v3
	v_cvt_pk_bf16_f32 v97, v4, v5
	v_cvt_pk_bf16_f32 v98, v6, v7
	v_cvt_pk_bf16_f32 v99, v8, v9
	s_waitcnt vmcnt(23)
	global_store_dwordx4 v108, v[96:99], s[16:17]
	s_add_u32 s16, s16, 0x100000
	s_addc_u32 s17, s17, 0
	v_lshlrev_b32_e32 v100, 16, v30
	v_and_b32_e32 v101, 0xffff0000, v30
	v_lshlrev_b32_e32 v102, 16, v31
	v_and_b32_e32 v103, 0xffff0000, v31
	v_lshlrev_b32_e32 v104, 16, v32
	v_and_b32_e32 v105, 0xffff0000, v32
	v_lshlrev_b32_e32 v106, 16, v33
	v_and_b32_e32 v107, 0xffff0000, v33
	s_waitcnt lgkmcnt(2)
	v_pk_fma_f32 v[2:3], v[2:3], v[84:85], v[100:101]
	v_pk_fma_f32 v[4:5], v[4:5], v[86:87], v[102:103]
	v_pk_fma_f32 v[6:7], v[6:7], v[88:89], v[104:105]
	v_pk_fma_f32 v[8:9], v[8:9], v[90:91], v[106:107]
	ds_read_b128 v[84:87], v109 offset:23552
	ds_read_b128 v[88:91], v109 offset:23568
	v_cvt_pk_bf16_f32 v92, v2, v3
	v_cvt_pk_bf16_f32 v93, v4, v5
	v_cvt_pk_bf16_f32 v94, v6, v7
	v_cvt_pk_bf16_f32 v95, v8, v9
	s_waitcnt vmcnt(23)
	global_store_dwordx4 v108, v[92:95], s[16:17]
	s_add_u32 s16, s16, 0x100000
	s_addc_u32 s17, s17, 0
	v_lshlrev_b32_e32 v100, 16, v34
	v_and_b32_e32 v101, 0xffff0000, v34
	v_lshlrev_b32_e32 v102, 16, v35
	v_and_b32_e32 v103, 0xffff0000, v35
	v_lshlrev_b32_e32 v104, 16, v36
	v_and_b32_e32 v105, 0xffff0000, v36
	v_lshlrev_b32_e32 v106, 16, v37
	v_and_b32_e32 v107, 0xffff0000, v37
	s_waitcnt lgkmcnt(2)
	v_pk_fma_f32 v[2:3], v[2:3], v[76:77], v[100:101]
	v_pk_fma_f32 v[4:5], v[4:5], v[78:79], v[102:103]
	v_pk_fma_f32 v[6:7], v[6:7], v[80:81], v[104:105]
	v_pk_fma_f32 v[8:9], v[8:9], v[82:83], v[106:107]
	ds_read_b128 v[76:79], v109 offset:24576
	ds_read_b128 v[80:83], v109 offset:24592
	v_cvt_pk_bf16_f32 v96, v2, v3
	v_cvt_pk_bf16_f32 v97, v4, v5
	v_cvt_pk_bf16_f32 v98, v6, v7
	v_cvt_pk_bf16_f32 v99, v8, v9
	s_waitcnt vmcnt(23)
	global_store_dwordx4 v108, v[96:99], s[16:17]
	s_add_u32 s16, s16, 0x100000
	s_addc_u32 s17, s17, 0
	v_lshlrev_b32_e32 v100, 16, v38
	v_and_b32_e32 v101, 0xffff0000, v38
	v_lshlrev_b32_e32 v102, 16, v39
	v_and_b32_e32 v103, 0xffff0000, v39
	v_lshlrev_b32_e32 v104, 16, v40
	v_and_b32_e32 v105, 0xffff0000, v40
	v_lshlrev_b32_e32 v106, 16, v41
	v_and_b32_e32 v107, 0xffff0000, v41
	s_waitcnt lgkmcnt(2)
	v_pk_fma_f32 v[2:3], v[2:3], v[84:85], v[100:101]
	v_pk_fma_f32 v[4:5], v[4:5], v[86:87], v[102:103]
	v_pk_fma_f32 v[6:7], v[6:7], v[88:89], v[104:105]
	v_pk_fma_f32 v[8:9], v[8:9], v[90:91], v[106:107]
	global_load_dwordx4 v[10:13], v108, s[12:13] nt
	s_add_u32 s12, s12, 0x100000
	s_addc_u32 s13, s13, 0
	global_load_dwordx4 v[14:17], v108, s[12:13] nt
	s_add_u32 s12, s12, 0x100000
	s_addc_u32 s13, s13, 0
	global_load_dwordx4 v[18:21], v108, s[12:13] nt
	s_add_u32 s12, s12, 0x100000
	s_addc_u32 s13, s13, 0
	global_load_dwordx4 v[22:25], v108, s[12:13] nt
	s_add_u32 s12, s12, 0x100000
	s_addc_u32 s13, s13, 0
	global_load_dwordx4 v[26:29], v108, s[12:13] nt
	s_add_u32 s12, s12, 0x100000
	s_addc_u32 s13, s13, 0
	global_load_dwordx4 v[30:33], v108, s[12:13] nt
	s_add_u32 s12, s12, 0x100000
	s_addc_u32 s13, s13, 0
	global_load_dwordx4 v[34:37], v108, s[12:13] nt
	s_add_u32 s12, s12, 0x100000
	s_addc_u32 s13, s13, 0
	global_load_dwordx4 v[38:41], v108, s[12:13] nt
	s_add_u32 s12, s12, 0x100000
	s_addc_u32 s13, s13, 0
	ds_read_b128 v[84:87], v109 offset:25600
	ds_read_b128 v[88:91], v109 offset:25616
	v_cvt_pk_bf16_f32 v92, v2, v3
	v_cvt_pk_bf16_f32 v93, v4, v5
	v_cvt_pk_bf16_f32 v94, v6, v7
	v_cvt_pk_bf16_f32 v95, v8, v9
	s_waitcnt vmcnt(23)
	global_store_dwordx4 v108, v[92:95], s[16:17]
	s_add_u32 s16, s16, 0x100000
	s_addc_u32 s17, s17, 0
	v_lshlrev_b32_e32 v100, 16, v42
	v_and_b32_e32 v101, 0xffff0000, v42
	v_lshlrev_b32_e32 v102, 16, v43
	v_and_b32_e32 v103, 0xffff0000, v43
	v_lshlrev_b32_e32 v104, 16, v44
	v_and_b32_e32 v105, 0xffff0000, v44
	v_lshlrev_b32_e32 v106, 16, v45
	v_and_b32_e32 v107, 0xffff0000, v45
	s_waitcnt lgkmcnt(2)
	v_pk_fma_f32 v[2:3], v[2:3], v[76:77], v[100:101]
	v_pk_fma_f32 v[4:5], v[4:5], v[78:79], v[102:103]
	v_pk_fma_f32 v[6:7], v[6:7], v[80:81], v[104:105]
	v_pk_fma_f32 v[8:9], v[8:9], v[82:83], v[106:107]
	ds_read_b128 v[76:79], v109 offset:26624
	ds_read_b128 v[80:83], v109 offset:26640
	v_cvt_pk_bf16_f32 v96, v2, v3
	v_cvt_pk_bf16_f32 v97, v4, v5
	v_cvt_pk_bf16_f32 v98, v6, v7
	v_cvt_pk_bf16_f32 v99, v8, v9
	s_waitcnt vmcnt(23)
	global_store_dwordx4 v108, v[96:99], s[16:17]
	s_add_u32 s16, s16, 0x100000
	s_addc_u32 s17, s17, 0
	v_lshlrev_b32_e32 v100, 16, v46
	v_and_b32_e32 v101, 0xffff0000, v46
	v_lshlrev_b32_e32 v102, 16, v47
	v_and_b32_e32 v103, 0xffff0000, v47
	v_lshlrev_b32_e32 v104, 16, v48
	v_and_b32_e32 v105, 0xffff0000, v48
	v_lshlrev_b32_e32 v106, 16, v49
	v_and_b32_e32 v107, 0xffff0000, v49
	s_waitcnt lgkmcnt(2)
	v_pk_fma_f32 v[2:3], v[2:3], v[84:85], v[100:101]
	v_pk_fma_f32 v[4:5], v[4:5], v[86:87], v[102:103]
	v_pk_fma_f32 v[6:7], v[6:7], v[88:89], v[104:105]
	v_pk_fma_f32 v[8:9], v[8:9], v[90:91], v[106:107]
	ds_read_b128 v[84:87], v109 offset:27648
	ds_read_b128 v[88:91], v109 offset:27664
	v_cvt_pk_bf16_f32 v92, v2, v3
	v_cvt_pk_bf16_f32 v93, v4, v5
	v_cvt_pk_bf16_f32 v94, v6, v7
	v_cvt_pk_bf16_f32 v95, v8, v9
	s_waitcnt vmcnt(23)
	global_store_dwordx4 v108, v[92:95], s[16:17]
	s_add_u32 s16, s16, 0x100000
	s_addc_u32 s17, s17, 0
	v_lshlrev_b32_e32 v100, 16, v50
	v_and_b32_e32 v101, 0xffff0000, v50
	v_lshlrev_b32_e32 v102, 16, v51
	v_and_b32_e32 v103, 0xffff0000, v51
	v_lshlrev_b32_e32 v104, 16, v52
	v_and_b32_e32 v105, 0xffff0000, v52
	v_lshlrev_b32_e32 v106, 16, v53
	v_and_b32_e32 v107, 0xffff0000, v53
	s_waitcnt lgkmcnt(2)
	v_pk_fma_f32 v[2:3], v[2:3], v[76:77], v[100:101]
	v_pk_fma_f32 v[4:5], v[4:5], v[78:79], v[102:103]
	v_pk_fma_f32 v[6:7], v[6:7], v[80:81], v[104:105]
	v_pk_fma_f32 v[8:9], v[8:9], v[82:83], v[106:107]
	ds_read_b128 v[76:79], v109 offset:28672
	ds_read_b128 v[80:83], v109 offset:28688
	v_cvt_pk_bf16_f32 v96, v2, v3
	v_cvt_pk_bf16_f32 v97, v4, v5
	v_cvt_pk_bf16_f32 v98, v6, v7
	v_cvt_pk_bf16_f32 v99, v8, v9
	s_waitcnt vmcnt(23)
	global_store_dwordx4 v108, v[96:99], s[16:17]
	s_add_u32 s16, s16, 0x100000
	s_addc_u32 s17, s17, 0
	v_lshlrev_b32_e32 v100, 16, v54
	v_and_b32_e32 v101, 0xffff0000, v54
	v_lshlrev_b32_e32 v102, 16, v55
	v_and_b32_e32 v103, 0xffff0000, v55
	v_lshlrev_b32_e32 v104, 16, v56
	v_and_b32_e32 v105, 0xffff0000, v56
	v_lshlrev_b32_e32 v106, 16, v57
	v_and_b32_e32 v107, 0xffff0000, v57
	s_waitcnt lgkmcnt(2)
	v_pk_fma_f32 v[2:3], v[2:3], v[84:85], v[100:101]
	v_pk_fma_f32 v[4:5], v[4:5], v[86:87], v[102:103]
	v_pk_fma_f32 v[6:7], v[6:7], v[88:89], v[104:105]
	v_pk_fma_f32 v[8:9], v[8:9], v[90:91], v[106:107]
	ds_read_b128 v[84:87], v109 offset:29696
	ds_read_b128 v[88:91], v109 offset:29712
	v_cvt_pk_bf16_f32 v92, v2, v3
	v_cvt_pk_bf16_f32 v93, v4, v5
	v_cvt_pk_bf16_f32 v94, v6, v7
	v_cvt_pk_bf16_f32 v95, v8, v9
	s_waitcnt vmcnt(23)
	global_store_dwordx4 v108, v[92:95], s[16:17]
	s_add_u32 s16, s16, 0x100000
	s_addc_u32 s17, s17, 0
	v_lshlrev_b32_e32 v100, 16, v58
	v_and_b32_e32 v101, 0xffff0000, v58
	v_lshlrev_b32_e32 v102, 16, v59
	v_and_b32_e32 v103, 0xffff0000, v59
	v_lshlrev_b32_e32 v104, 16, v60
	v_and_b32_e32 v105, 0xffff0000, v60
	v_lshlrev_b32_e32 v106, 16, v61
	v_and_b32_e32 v107, 0xffff0000, v61
	s_waitcnt lgkmcnt(2)
	v_pk_fma_f32 v[2:3], v[2:3], v[76:77], v[100:101]
	v_pk_fma_f32 v[4:5], v[4:5], v[78:79], v[102:103]
	v_pk_fma_f32 v[6:7], v[6:7], v[80:81], v[104:105]
	v_pk_fma_f32 v[8:9], v[8:9], v[82:83], v[106:107]
	ds_read_b128 v[76:79], v109 offset:30720
	ds_read_b128 v[80:83], v109 offset:30736
	v_cvt_pk_bf16_f32 v96, v2, v3
	v_cvt_pk_bf16_f32 v97, v4, v5
	v_cvt_pk_bf16_f32 v98, v6, v7
	v_cvt_pk_bf16_f32 v99, v8, v9
	s_waitcnt vmcnt(23)
	global_store_dwordx4 v108, v[96:99], s[16:17]
	s_add_u32 s16, s16, 0x100000
	s_addc_u32 s17, s17, 0
	v_lshlrev_b32_e32 v100, 16, v62
	v_and_b32_e32 v101, 0xffff0000, v62
	v_lshlrev_b32_e32 v102, 16, v63
	v_and_b32_e32 v103, 0xffff0000, v63
	v_lshlrev_b32_e32 v104, 16, v64
	v_and_b32_e32 v105, 0xffff0000, v64
	v_lshlrev_b32_e32 v106, 16, v65
	v_and_b32_e32 v107, 0xffff0000, v65
	s_waitcnt lgkmcnt(2)
	v_pk_fma_f32 v[2:3], v[2:3], v[84:85], v[100:101]
	v_pk_fma_f32 v[4:5], v[4:5], v[86:87], v[102:103]
	v_pk_fma_f32 v[6:7], v[6:7], v[88:89], v[104:105]
	v_pk_fma_f32 v[8:9], v[8:9], v[90:91], v[106:107]
	ds_read_b128 v[84:87], v109 offset:31744
	ds_read_b128 v[88:91], v109 offset:31760
	v_cvt_pk_bf16_f32 v92, v2, v3
	v_cvt_pk_bf16_f32 v93, v4, v5
	v_cvt_pk_bf16_f32 v94, v6, v7
	v_cvt_pk_bf16_f32 v95, v8, v9
	s_waitcnt vmcnt(23)
	global_store_dwordx4 v108, v[92:95], s[16:17]
	s_add_u32 s16, s16, 0x100000
	s_addc_u32 s17, s17, 0
	v_lshlrev_b32_e32 v100, 16, v68
	v_and_b32_e32 v101, 0xffff0000, v68
	v_lshlrev_b32_e32 v102, 16, v69
	v_and_b32_e32 v103, 0xffff0000, v69
	v_lshlrev_b32_e32 v104, 16, v70
	v_and_b32_e32 v105, 0xffff0000, v70
	v_lshlrev_b32_e32 v106, 16, v71
	v_and_b32_e32 v107, 0xffff0000, v71
	s_waitcnt lgkmcnt(2)
	v_pk_fma_f32 v[2:3], v[2:3], v[76:77], v[100:101]
	v_pk_fma_f32 v[4:5], v[4:5], v[78:79], v[102:103]
	v_pk_fma_f32 v[6:7], v[6:7], v[80:81], v[104:105]
	v_pk_fma_f32 v[8:9], v[8:9], v[82:83], v[106:107]
	ds_read_b128 v[76:79], v109 offset:32768
	ds_read_b128 v[80:83], v109 offset:32784
	v_cvt_pk_bf16_f32 v96, v2, v3
	v_cvt_pk_bf16_f32 v97, v4, v5
	v_cvt_pk_bf16_f32 v98, v6, v7
	v_cvt_pk_bf16_f32 v99, v8, v9
	s_waitcnt vmcnt(23)
	global_store_dwordx4 v108, v[96:99], s[16:17]
	s_add_u32 s16, s16, 0x100000
	s_addc_u32 s17, s17, 0
	v_lshlrev_b32_e32 v100, 16, v72
	v_and_b32_e32 v101, 0xffff0000, v72
	v_lshlrev_b32_e32 v102, 16, v73
	v_and_b32_e32 v103, 0xffff0000, v73
	v_lshlrev_b32_e32 v104, 16, v74
	v_and_b32_e32 v105, 0xffff0000, v74
	v_lshlrev_b32_e32 v106, 16, v75
	v_and_b32_e32 v107, 0xffff0000, v75
	s_waitcnt lgkmcnt(2)
	v_pk_fma_f32 v[2:3], v[2:3], v[84:85], v[100:101]
	v_pk_fma_f32 v[4:5], v[4:5], v[86:87], v[102:103]
	v_pk_fma_f32 v[6:7], v[6:7], v[88:89], v[104:105]
	v_pk_fma_f32 v[8:9], v[8:9], v[90:91], v[106:107]
	global_load_dwordx4 v[42:45], v108, s[12:13] nt
	s_add_u32 s12, s12, 0x100000
	s_addc_u32 s13, s13, 0
	global_load_dwordx4 v[46:49], v108, s[12:13] nt
	s_add_u32 s12, s12, 0x100000
	s_addc_u32 s13, s13, 0
	global_load_dwordx4 v[50:53], v108, s[12:13] nt
	s_add_u32 s12, s12, 0x100000
	s_addc_u32 s13, s13, 0
	global_load_dwordx4 v[54:57], v108, s[12:13] nt
	s_add_u32 s12, s12, 0x100000
	s_addc_u32 s13, s13, 0
	global_load_dwordx4 v[58:61], v108, s[12:13] nt
	s_add_u32 s12, s12, 0x100000
	s_addc_u32 s13, s13, 0
	global_load_dwordx4 v[62:65], v108, s[12:13] nt
	s_add_u32 s12, s12, 0x100000
	s_addc_u32 s13, s13, 0
	global_load_dwordx4 v[68:71], v108, s[12:13] nt
	s_add_u32 s12, s12, 0x100000
	s_addc_u32 s13, s13, 0
	global_load_dwordx4 v[72:75], v108, s[12:13] nt
	s_add_u32 s12, s12, 0x100000
	s_addc_u32 s13, s13, 0
	ds_read_b128 v[84:87], v109 offset:33792
	ds_read_b128 v[88:91], v109 offset:33808
	v_cvt_pk_bf16_f32 v92, v2, v3
	v_cvt_pk_bf16_f32 v93, v4, v5
	v_cvt_pk_bf16_f32 v94, v6, v7
	v_cvt_pk_bf16_f32 v95, v8, v9
	s_waitcnt vmcnt(23)
	global_store_dwordx4 v108, v[92:95], s[16:17]
	s_add_u32 s16, s16, 0x100000
	s_addc_u32 s17, s17, 0
	v_lshlrev_b32_e32 v100, 16, v10
	v_and_b32_e32 v101, 0xffff0000, v10
	v_lshlrev_b32_e32 v102, 16, v11
	v_and_b32_e32 v103, 0xffff0000, v11
	v_lshlrev_b32_e32 v104, 16, v12
	v_and_b32_e32 v105, 0xffff0000, v12
	v_lshlrev_b32_e32 v106, 16, v13
	v_and_b32_e32 v107, 0xffff0000, v13
	s_waitcnt lgkmcnt(2)
	v_pk_fma_f32 v[2:3], v[2:3], v[76:77], v[100:101]
	v_pk_fma_f32 v[4:5], v[4:5], v[78:79], v[102:103]
	v_pk_fma_f32 v[6:7], v[6:7], v[80:81], v[104:105]
	v_pk_fma_f32 v[8:9], v[8:9], v[82:83], v[106:107]
	ds_read_b128 v[76:79], v109 offset:34816
	ds_read_b128 v[80:83], v109 offset:34832
	v_cvt_pk_bf16_f32 v96, v2, v3
	v_cvt_pk_bf16_f32 v97, v4, v5
	v_cvt_pk_bf16_f32 v98, v6, v7
	v_cvt_pk_bf16_f32 v99, v8, v9
	s_waitcnt vmcnt(23)
	global_store_dwordx4 v108, v[96:99], s[16:17]
	s_add_u32 s16, s16, 0x100000
	s_addc_u32 s17, s17, 0
	v_lshlrev_b32_e32 v100, 16, v14
	v_and_b32_e32 v101, 0xffff0000, v14
	v_lshlrev_b32_e32 v102, 16, v15
	v_and_b32_e32 v103, 0xffff0000, v15
	v_lshlrev_b32_e32 v104, 16, v16
	v_and_b32_e32 v105, 0xffff0000, v16
	v_lshlrev_b32_e32 v106, 16, v17
	v_and_b32_e32 v107, 0xffff0000, v17
	s_waitcnt lgkmcnt(2)
	v_pk_fma_f32 v[2:3], v[2:3], v[84:85], v[100:101]
	v_pk_fma_f32 v[4:5], v[4:5], v[86:87], v[102:103]
	v_pk_fma_f32 v[6:7], v[6:7], v[88:89], v[104:105]
	v_pk_fma_f32 v[8:9], v[8:9], v[90:91], v[106:107]
	ds_read_b128 v[84:87], v109 offset:35840
	ds_read_b128 v[88:91], v109 offset:35856
	v_cvt_pk_bf16_f32 v92, v2, v3
	v_cvt_pk_bf16_f32 v93, v4, v5
	v_cvt_pk_bf16_f32 v94, v6, v7
	v_cvt_pk_bf16_f32 v95, v8, v9
	s_waitcnt vmcnt(23)
	global_store_dwordx4 v108, v[92:95], s[16:17]
	s_add_u32 s16, s16, 0x100000
	s_addc_u32 s17, s17, 0
	v_lshlrev_b32_e32 v100, 16, v18
	v_and_b32_e32 v101, 0xffff0000, v18
	v_lshlrev_b32_e32 v102, 16, v19
	v_and_b32_e32 v103, 0xffff0000, v19
	v_lshlrev_b32_e32 v104, 16, v20
	v_and_b32_e32 v105, 0xffff0000, v20
	v_lshlrev_b32_e32 v106, 16, v21
	v_and_b32_e32 v107, 0xffff0000, v21
	s_waitcnt lgkmcnt(2)
	v_pk_fma_f32 v[2:3], v[2:3], v[76:77], v[100:101]
	v_pk_fma_f32 v[4:5], v[4:5], v[78:79], v[102:103]
	v_pk_fma_f32 v[6:7], v[6:7], v[80:81], v[104:105]
	v_pk_fma_f32 v[8:9], v[8:9], v[82:83], v[106:107]
	ds_read_b128 v[76:79], v109 offset:36864
	ds_read_b128 v[80:83], v109 offset:36880
	v_cvt_pk_bf16_f32 v96, v2, v3
	v_cvt_pk_bf16_f32 v97, v4, v5
	v_cvt_pk_bf16_f32 v98, v6, v7
	v_cvt_pk_bf16_f32 v99, v8, v9
	s_waitcnt vmcnt(23)
	global_store_dwordx4 v108, v[96:99], s[16:17]
	s_add_u32 s16, s16, 0x100000
	s_addc_u32 s17, s17, 0
	v_lshlrev_b32_e32 v100, 16, v22
	v_and_b32_e32 v101, 0xffff0000, v22
	v_lshlrev_b32_e32 v102, 16, v23
	v_and_b32_e32 v103, 0xffff0000, v23
	v_lshlrev_b32_e32 v104, 16, v24
	v_and_b32_e32 v105, 0xffff0000, v24
	v_lshlrev_b32_e32 v106, 16, v25
	v_and_b32_e32 v107, 0xffff0000, v25
	s_waitcnt lgkmcnt(2)
	v_pk_fma_f32 v[2:3], v[2:3], v[84:85], v[100:101]
	v_pk_fma_f32 v[4:5], v[4:5], v[86:87], v[102:103]
	v_pk_fma_f32 v[6:7], v[6:7], v[88:89], v[104:105]
	v_pk_fma_f32 v[8:9], v[8:9], v[90:91], v[106:107]
	ds_read_b128 v[84:87], v109 offset:37888
	ds_read_b128 v[88:91], v109 offset:37904
	v_cvt_pk_bf16_f32 v92, v2, v3
	v_cvt_pk_bf16_f32 v93, v4, v5
	v_cvt_pk_bf16_f32 v94, v6, v7
	v_cvt_pk_bf16_f32 v95, v8, v9
	s_waitcnt vmcnt(23)
	global_store_dwordx4 v108, v[92:95], s[16:17]
	s_add_u32 s16, s16, 0x100000
	s_addc_u32 s17, s17, 0
	v_lshlrev_b32_e32 v100, 16, v26
	v_and_b32_e32 v101, 0xffff0000, v26
	v_lshlrev_b32_e32 v102, 16, v27
	v_and_b32_e32 v103, 0xffff0000, v27
	v_lshlrev_b32_e32 v104, 16, v28
	v_and_b32_e32 v105, 0xffff0000, v28
	v_lshlrev_b32_e32 v106, 16, v29
	v_and_b32_e32 v107, 0xffff0000, v29
	s_waitcnt lgkmcnt(2)
	v_pk_fma_f32 v[2:3], v[2:3], v[76:77], v[100:101]
	v_pk_fma_f32 v[4:5], v[4:5], v[78:79], v[102:103]
	v_pk_fma_f32 v[6:7], v[6:7], v[80:81], v[104:105]
	v_pk_fma_f32 v[8:9], v[8:9], v[82:83], v[106:107]
	ds_read_b128 v[76:79], v109 offset:38912
	ds_read_b128 v[80:83], v109 offset:38928
	v_cvt_pk_bf16_f32 v96, v2, v3
	v_cvt_pk_bf16_f32 v97, v4, v5
	v_cvt_pk_bf16_f32 v98, v6, v7
	v_cvt_pk_bf16_f32 v99, v8, v9
	s_waitcnt vmcnt(23)
	global_store_dwordx4 v108, v[96:99], s[16:17]
	s_add_u32 s16, s16, 0x100000
	s_addc_u32 s17, s17, 0
	v_lshlrev_b32_e32 v100, 16, v30
	v_and_b32_e32 v101, 0xffff0000, v30
	v_lshlrev_b32_e32 v102, 16, v31
	v_and_b32_e32 v103, 0xffff0000, v31
	v_lshlrev_b32_e32 v104, 16, v32
	v_and_b32_e32 v105, 0xffff0000, v32
	v_lshlrev_b32_e32 v106, 16, v33
	v_and_b32_e32 v107, 0xffff0000, v33
	s_waitcnt lgkmcnt(2)
	v_pk_fma_f32 v[2:3], v[2:3], v[84:85], v[100:101]
	v_pk_fma_f32 v[4:5], v[4:5], v[86:87], v[102:103]
	v_pk_fma_f32 v[6:7], v[6:7], v[88:89], v[104:105]
	v_pk_fma_f32 v[8:9], v[8:9], v[90:91], v[106:107]
	ds_read_b128 v[84:87], v109 offset:39936
	ds_read_b128 v[88:91], v109 offset:39952
	v_cvt_pk_bf16_f32 v92, v2, v3
	v_cvt_pk_bf16_f32 v93, v4, v5
	v_cvt_pk_bf16_f32 v94, v6, v7
	v_cvt_pk_bf16_f32 v95, v8, v9
	s_waitcnt vmcnt(23)
	global_store_dwordx4 v108, v[92:95], s[16:17]
	s_add_u32 s16, s16, 0x100000
	s_addc_u32 s17, s17, 0
	v_lshlrev_b32_e32 v100, 16, v34
	v_and_b32_e32 v101, 0xffff0000, v34
	v_lshlrev_b32_e32 v102, 16, v35
	v_and_b32_e32 v103, 0xffff0000, v35
	v_lshlrev_b32_e32 v104, 16, v36
	v_and_b32_e32 v105, 0xffff0000, v36
	v_lshlrev_b32_e32 v106, 16, v37
	v_and_b32_e32 v107, 0xffff0000, v37
	s_waitcnt lgkmcnt(2)
	v_pk_fma_f32 v[2:3], v[2:3], v[76:77], v[100:101]
	v_pk_fma_f32 v[4:5], v[4:5], v[78:79], v[102:103]
	v_pk_fma_f32 v[6:7], v[6:7], v[80:81], v[104:105]
	v_pk_fma_f32 v[8:9], v[8:9], v[82:83], v[106:107]
	ds_read_b128 v[76:79], v109 offset:40960
	ds_read_b128 v[80:83], v109 offset:40976
	v_cvt_pk_bf16_f32 v96, v2, v3
	v_cvt_pk_bf16_f32 v97, v4, v5
	v_cvt_pk_bf16_f32 v98, v6, v7
	v_cvt_pk_bf16_f32 v99, v8, v9
	s_waitcnt vmcnt(23)
	global_store_dwordx4 v108, v[96:99], s[16:17]
	s_add_u32 s16, s16, 0x100000
	s_addc_u32 s17, s17, 0
	v_lshlrev_b32_e32 v100, 16, v38
	v_and_b32_e32 v101, 0xffff0000, v38
	v_lshlrev_b32_e32 v102, 16, v39
	v_and_b32_e32 v103, 0xffff0000, v39
	v_lshlrev_b32_e32 v104, 16, v40
	v_and_b32_e32 v105, 0xffff0000, v40
	v_lshlrev_b32_e32 v106, 16, v41
	v_and_b32_e32 v107, 0xffff0000, v41
	s_waitcnt lgkmcnt(2)
	v_pk_fma_f32 v[2:3], v[2:3], v[84:85], v[100:101]
	v_pk_fma_f32 v[4:5], v[4:5], v[86:87], v[102:103]
	v_pk_fma_f32 v[6:7], v[6:7], v[88:89], v[104:105]
	v_pk_fma_f32 v[8:9], v[8:9], v[90:91], v[106:107]
	global_load_dwordx4 v[10:13], v108, s[12:13] nt
	s_add_u32 s12, s12, 0x100000
	s_addc_u32 s13, s13, 0
	global_load_dwordx4 v[14:17], v108, s[12:13] nt
	s_add_u32 s12, s12, 0x100000
	s_addc_u32 s13, s13, 0
	global_load_dwordx4 v[18:21], v108, s[12:13] nt
	s_add_u32 s12, s12, 0x100000
	s_addc_u32 s13, s13, 0
	global_load_dwordx4 v[22:25], v108, s[12:13] nt
	s_add_u32 s12, s12, 0x100000
	s_addc_u32 s13, s13, 0
	global_load_dwordx4 v[26:29], v108, s[12:13] nt
	s_add_u32 s12, s12, 0x100000
	s_addc_u32 s13, s13, 0
	global_load_dwordx4 v[30:33], v108, s[12:13] nt
	s_add_u32 s12, s12, 0x100000
	s_addc_u32 s13, s13, 0
	global_load_dwordx4 v[34:37], v108, s[12:13] nt
	s_add_u32 s12, s12, 0x100000
	s_addc_u32 s13, s13, 0
	global_load_dwordx4 v[38:41], v108, s[12:13] nt
	s_add_u32 s12, s12, 0x100000
	s_addc_u32 s13, s13, 0
	ds_read_b128 v[84:87], v109 offset:41984
	ds_read_b128 v[88:91], v109 offset:42000
	v_cvt_pk_bf16_f32 v92, v2, v3
	v_cvt_pk_bf16_f32 v93, v4, v5
	v_cvt_pk_bf16_f32 v94, v6, v7
	v_cvt_pk_bf16_f32 v95, v8, v9
	s_waitcnt vmcnt(23)
	global_store_dwordx4 v108, v[92:95], s[16:17]
	s_add_u32 s16, s16, 0x100000
	s_addc_u32 s17, s17, 0
	v_lshlrev_b32_e32 v100, 16, v42
	v_and_b32_e32 v101, 0xffff0000, v42
	v_lshlrev_b32_e32 v102, 16, v43
	v_and_b32_e32 v103, 0xffff0000, v43
	v_lshlrev_b32_e32 v104, 16, v44
	v_and_b32_e32 v105, 0xffff0000, v44
	v_lshlrev_b32_e32 v106, 16, v45
	v_and_b32_e32 v107, 0xffff0000, v45
	s_waitcnt lgkmcnt(2)
	v_pk_fma_f32 v[2:3], v[2:3], v[76:77], v[100:101]
	v_pk_fma_f32 v[4:5], v[4:5], v[78:79], v[102:103]
	v_pk_fma_f32 v[6:7], v[6:7], v[80:81], v[104:105]
	v_pk_fma_f32 v[8:9], v[8:9], v[82:83], v[106:107]
	ds_read_b128 v[76:79], v109 offset:43008
	ds_read_b128 v[80:83], v109 offset:43024
	v_cvt_pk_bf16_f32 v96, v2, v3
	v_cvt_pk_bf16_f32 v97, v4, v5
	v_cvt_pk_bf16_f32 v98, v6, v7
	v_cvt_pk_bf16_f32 v99, v8, v9
	s_waitcnt vmcnt(23)
	global_store_dwordx4 v108, v[96:99], s[16:17]
	s_add_u32 s16, s16, 0x100000
	s_addc_u32 s17, s17, 0
	v_lshlrev_b32_e32 v100, 16, v46
	v_and_b32_e32 v101, 0xffff0000, v46
	v_lshlrev_b32_e32 v102, 16, v47
	v_and_b32_e32 v103, 0xffff0000, v47
	v_lshlrev_b32_e32 v104, 16, v48
	v_and_b32_e32 v105, 0xffff0000, v48
	v_lshlrev_b32_e32 v106, 16, v49
	v_and_b32_e32 v107, 0xffff0000, v49
	s_waitcnt lgkmcnt(2)
	v_pk_fma_f32 v[2:3], v[2:3], v[84:85], v[100:101]
	v_pk_fma_f32 v[4:5], v[4:5], v[86:87], v[102:103]
	v_pk_fma_f32 v[6:7], v[6:7], v[88:89], v[104:105]
	v_pk_fma_f32 v[8:9], v[8:9], v[90:91], v[106:107]
	ds_read_b128 v[84:87], v109 offset:44032
	ds_read_b128 v[88:91], v109 offset:44048
	v_cvt_pk_bf16_f32 v92, v2, v3
	v_cvt_pk_bf16_f32 v93, v4, v5
	v_cvt_pk_bf16_f32 v94, v6, v7
	v_cvt_pk_bf16_f32 v95, v8, v9
	s_waitcnt vmcnt(23)
	global_store_dwordx4 v108, v[92:95], s[16:17]
	s_add_u32 s16, s16, 0x100000
	s_addc_u32 s17, s17, 0
	v_lshlrev_b32_e32 v100, 16, v50
	v_and_b32_e32 v101, 0xffff0000, v50
	v_lshlrev_b32_e32 v102, 16, v51
	v_and_b32_e32 v103, 0xffff0000, v51
	v_lshlrev_b32_e32 v104, 16, v52
	v_and_b32_e32 v105, 0xffff0000, v52
	v_lshlrev_b32_e32 v106, 16, v53
	v_and_b32_e32 v107, 0xffff0000, v53
	s_waitcnt lgkmcnt(2)
	v_pk_fma_f32 v[2:3], v[2:3], v[76:77], v[100:101]
	v_pk_fma_f32 v[4:5], v[4:5], v[78:79], v[102:103]
	v_pk_fma_f32 v[6:7], v[6:7], v[80:81], v[104:105]
	v_pk_fma_f32 v[8:9], v[8:9], v[82:83], v[106:107]
	ds_read_b128 v[76:79], v109 offset:45056
	ds_read_b128 v[80:83], v109 offset:45072
	v_cvt_pk_bf16_f32 v96, v2, v3
	v_cvt_pk_bf16_f32 v97, v4, v5
	v_cvt_pk_bf16_f32 v98, v6, v7
	v_cvt_pk_bf16_f32 v99, v8, v9
	s_waitcnt vmcnt(23)
	global_store_dwordx4 v108, v[96:99], s[16:17]
	s_add_u32 s16, s16, 0x100000
	s_addc_u32 s17, s17, 0
	v_lshlrev_b32_e32 v100, 16, v54
	v_and_b32_e32 v101, 0xffff0000, v54
	v_lshlrev_b32_e32 v102, 16, v55
	v_and_b32_e32 v103, 0xffff0000, v55
	v_lshlrev_b32_e32 v104, 16, v56
	v_and_b32_e32 v105, 0xffff0000, v56
	v_lshlrev_b32_e32 v106, 16, v57
	v_and_b32_e32 v107, 0xffff0000, v57
	s_waitcnt lgkmcnt(2)
	v_pk_fma_f32 v[2:3], v[2:3], v[84:85], v[100:101]
	v_pk_fma_f32 v[4:5], v[4:5], v[86:87], v[102:103]
	v_pk_fma_f32 v[6:7], v[6:7], v[88:89], v[104:105]
	v_pk_fma_f32 v[8:9], v[8:9], v[90:91], v[106:107]
	ds_read_b128 v[84:87], v109 offset:46080
	ds_read_b128 v[88:91], v109 offset:46096
	v_cvt_pk_bf16_f32 v92, v2, v3
	v_cvt_pk_bf16_f32 v93, v4, v5
	v_cvt_pk_bf16_f32 v94, v6, v7
	v_cvt_pk_bf16_f32 v95, v8, v9
	s_waitcnt vmcnt(23)
	global_store_dwordx4 v108, v[92:95], s[16:17]
	s_add_u32 s16, s16, 0x100000
	s_addc_u32 s17, s17, 0
	v_lshlrev_b32_e32 v100, 16, v58
	v_and_b32_e32 v101, 0xffff0000, v58
	v_lshlrev_b32_e32 v102, 16, v59
	v_and_b32_e32 v103, 0xffff0000, v59
	v_lshlrev_b32_e32 v104, 16, v60
	v_and_b32_e32 v105, 0xffff0000, v60
	v_lshlrev_b32_e32 v106, 16, v61
	v_and_b32_e32 v107, 0xffff0000, v61
	s_waitcnt lgkmcnt(2)
	v_pk_fma_f32 v[2:3], v[2:3], v[76:77], v[100:101]
	v_pk_fma_f32 v[4:5], v[4:5], v[78:79], v[102:103]
	v_pk_fma_f32 v[6:7], v[6:7], v[80:81], v[104:105]
	v_pk_fma_f32 v[8:9], v[8:9], v[82:83], v[106:107]
	ds_read_b128 v[76:79], v109 offset:47104
	ds_read_b128 v[80:83], v109 offset:47120
	v_cvt_pk_bf16_f32 v96, v2, v3
	v_cvt_pk_bf16_f32 v97, v4, v5
	v_cvt_pk_bf16_f32 v98, v6, v7
	v_cvt_pk_bf16_f32 v99, v8, v9
	s_waitcnt vmcnt(23)
	global_store_dwordx4 v108, v[96:99], s[16:17]
	s_add_u32 s16, s16, 0x100000
	s_addc_u32 s17, s17, 0
	v_lshlrev_b32_e32 v100, 16, v62
	v_and_b32_e32 v101, 0xffff0000, v62
	v_lshlrev_b32_e32 v102, 16, v63
	v_and_b32_e32 v103, 0xffff0000, v63
	v_lshlrev_b32_e32 v104, 16, v64
	v_and_b32_e32 v105, 0xffff0000, v64
	v_lshlrev_b32_e32 v106, 16, v65
	v_and_b32_e32 v107, 0xffff0000, v65
	s_waitcnt lgkmcnt(2)
	v_pk_fma_f32 v[2:3], v[2:3], v[84:85], v[100:101]
	v_pk_fma_f32 v[4:5], v[4:5], v[86:87], v[102:103]
	v_pk_fma_f32 v[6:7], v[6:7], v[88:89], v[104:105]
	v_pk_fma_f32 v[8:9], v[8:9], v[90:91], v[106:107]
	ds_read_b128 v[84:87], v109 offset:48128
	ds_read_b128 v[88:91], v109 offset:48144
	v_cvt_pk_bf16_f32 v92, v2, v3
	v_cvt_pk_bf16_f32 v93, v4, v5
	v_cvt_pk_bf16_f32 v94, v6, v7
	v_cvt_pk_bf16_f32 v95, v8, v9
	s_waitcnt vmcnt(23)
	global_store_dwordx4 v108, v[92:95], s[16:17]
	s_add_u32 s16, s16, 0x100000
	s_addc_u32 s17, s17, 0
	v_lshlrev_b32_e32 v100, 16, v68
	v_and_b32_e32 v101, 0xffff0000, v68
	v_lshlrev_b32_e32 v102, 16, v69
	v_and_b32_e32 v103, 0xffff0000, v69
	v_lshlrev_b32_e32 v104, 16, v70
	v_and_b32_e32 v105, 0xffff0000, v70
	v_lshlrev_b32_e32 v106, 16, v71
	v_and_b32_e32 v107, 0xffff0000, v71
	s_waitcnt lgkmcnt(2)
	v_pk_fma_f32 v[2:3], v[2:3], v[76:77], v[100:101]
	v_pk_fma_f32 v[4:5], v[4:5], v[78:79], v[102:103]
	v_pk_fma_f32 v[6:7], v[6:7], v[80:81], v[104:105]
	v_pk_fma_f32 v[8:9], v[8:9], v[82:83], v[106:107]
	ds_read_b128 v[76:79], v109 offset:49152
	ds_read_b128 v[80:83], v109 offset:49168
	v_cvt_pk_bf16_f32 v96, v2, v3
	v_cvt_pk_bf16_f32 v97, v4, v5
	v_cvt_pk_bf16_f32 v98, v6, v7
	v_cvt_pk_bf16_f32 v99, v8, v9
	s_waitcnt vmcnt(23)
	global_store_dwordx4 v108, v[96:99], s[16:17]
	s_add_u32 s16, s16, 0x100000
	s_addc_u32 s17, s17, 0
	v_lshlrev_b32_e32 v100, 16, v72
	v_and_b32_e32 v101, 0xffff0000, v72
	v_lshlrev_b32_e32 v102, 16, v73
	v_and_b32_e32 v103, 0xffff0000, v73
	v_lshlrev_b32_e32 v104, 16, v74
	v_and_b32_e32 v105, 0xffff0000, v74
	v_lshlrev_b32_e32 v106, 16, v75
	v_and_b32_e32 v107, 0xffff0000, v75
	s_waitcnt lgkmcnt(2)
	v_pk_fma_f32 v[2:3], v[2:3], v[84:85], v[100:101]
	v_pk_fma_f32 v[4:5], v[4:5], v[86:87], v[102:103]
	v_pk_fma_f32 v[6:7], v[6:7], v[88:89], v[104:105]
	v_pk_fma_f32 v[8:9], v[8:9], v[90:91], v[106:107]
	global_load_dwordx4 v[42:45], v108, s[12:13] nt
	s_add_u32 s12, s12, 0x100000
	s_addc_u32 s13, s13, 0
	global_load_dwordx4 v[46:49], v108, s[12:13] nt
	s_add_u32 s12, s12, 0x100000
	s_addc_u32 s13, s13, 0
	global_load_dwordx4 v[50:53], v108, s[12:13] nt
	s_add_u32 s12, s12, 0x100000
	s_addc_u32 s13, s13, 0
	global_load_dwordx4 v[54:57], v108, s[12:13] nt
	s_add_u32 s12, s12, 0x100000
	s_addc_u32 s13, s13, 0
	global_load_dwordx4 v[58:61], v108, s[12:13] nt
	s_add_u32 s12, s12, 0x100000
	s_addc_u32 s13, s13, 0
	global_load_dwordx4 v[62:65], v108, s[12:13] nt
	s_add_u32 s12, s12, 0x100000
	s_addc_u32 s13, s13, 0
	global_load_dwordx4 v[68:71], v108, s[12:13] nt
	s_add_u32 s12, s12, 0x100000
	s_addc_u32 s13, s13, 0
	global_load_dwordx4 v[72:75], v108, s[12:13] nt
	s_add_u32 s12, s12, 0x100000
	s_addc_u32 s13, s13, 0
	ds_read_b128 v[84:87], v109 offset:50176
	ds_read_b128 v[88:91], v109 offset:50192
	v_cvt_pk_bf16_f32 v92, v2, v3
	v_cvt_pk_bf16_f32 v93, v4, v5
	v_cvt_pk_bf16_f32 v94, v6, v7
	v_cvt_pk_bf16_f32 v95, v8, v9
	s_waitcnt vmcnt(23)
	global_store_dwordx4 v108, v[92:95], s[16:17]
	s_add_u32 s16, s16, 0x100000
	s_addc_u32 s17, s17, 0
	v_lshlrev_b32_e32 v100, 16, v10
	v_and_b32_e32 v101, 0xffff0000, v10
	v_lshlrev_b32_e32 v102, 16, v11
	v_and_b32_e32 v103, 0xffff0000, v11
	v_lshlrev_b32_e32 v104, 16, v12
	v_and_b32_e32 v105, 0xffff0000, v12
	v_lshlrev_b32_e32 v106, 16, v13
	v_and_b32_e32 v107, 0xffff0000, v13
	s_waitcnt lgkmcnt(2)
	v_pk_fma_f32 v[2:3], v[2:3], v[76:77], v[100:101]
	v_pk_fma_f32 v[4:5], v[4:5], v[78:79], v[102:103]
	v_pk_fma_f32 v[6:7], v[6:7], v[80:81], v[104:105]
	v_pk_fma_f32 v[8:9], v[8:9], v[82:83], v[106:107]
	ds_read_b128 v[76:79], v109 offset:51200
	ds_read_b128 v[80:83], v109 offset:51216
	v_cvt_pk_bf16_f32 v96, v2, v3
	v_cvt_pk_bf16_f32 v97, v4, v5
	v_cvt_pk_bf16_f32 v98, v6, v7
	v_cvt_pk_bf16_f32 v99, v8, v9
	s_waitcnt vmcnt(23)
	global_store_dwordx4 v108, v[96:99], s[16:17]
	s_add_u32 s16, s16, 0x100000
	s_addc_u32 s17, s17, 0
	v_lshlrev_b32_e32 v100, 16, v14
	v_and_b32_e32 v101, 0xffff0000, v14
	v_lshlrev_b32_e32 v102, 16, v15
	v_and_b32_e32 v103, 0xffff0000, v15
	v_lshlrev_b32_e32 v104, 16, v16
	v_and_b32_e32 v105, 0xffff0000, v16
	v_lshlrev_b32_e32 v106, 16, v17
	v_and_b32_e32 v107, 0xffff0000, v17
	s_waitcnt lgkmcnt(2)
	v_pk_fma_f32 v[2:3], v[2:3], v[84:85], v[100:101]
	v_pk_fma_f32 v[4:5], v[4:5], v[86:87], v[102:103]
	v_pk_fma_f32 v[6:7], v[6:7], v[88:89], v[104:105]
	v_pk_fma_f32 v[8:9], v[8:9], v[90:91], v[106:107]
	ds_read_b128 v[84:87], v109 offset:52224
	ds_read_b128 v[88:91], v109 offset:52240
	v_cvt_pk_bf16_f32 v92, v2, v3
	v_cvt_pk_bf16_f32 v93, v4, v5
	v_cvt_pk_bf16_f32 v94, v6, v7
	v_cvt_pk_bf16_f32 v95, v8, v9
	s_waitcnt vmcnt(23)
	global_store_dwordx4 v108, v[92:95], s[16:17]
	s_add_u32 s16, s16, 0x100000
	s_addc_u32 s17, s17, 0
	v_lshlrev_b32_e32 v100, 16, v18
	v_and_b32_e32 v101, 0xffff0000, v18
	v_lshlrev_b32_e32 v102, 16, v19
	v_and_b32_e32 v103, 0xffff0000, v19
	v_lshlrev_b32_e32 v104, 16, v20
	v_and_b32_e32 v105, 0xffff0000, v20
	v_lshlrev_b32_e32 v106, 16, v21
	v_and_b32_e32 v107, 0xffff0000, v21
	s_waitcnt lgkmcnt(2)
	v_pk_fma_f32 v[2:3], v[2:3], v[76:77], v[100:101]
	v_pk_fma_f32 v[4:5], v[4:5], v[78:79], v[102:103]
	v_pk_fma_f32 v[6:7], v[6:7], v[80:81], v[104:105]
	v_pk_fma_f32 v[8:9], v[8:9], v[82:83], v[106:107]
	ds_read_b128 v[76:79], v109 offset:53248
	ds_read_b128 v[80:83], v109 offset:53264
	v_cvt_pk_bf16_f32 v96, v2, v3
	v_cvt_pk_bf16_f32 v97, v4, v5
	v_cvt_pk_bf16_f32 v98, v6, v7
	v_cvt_pk_bf16_f32 v99, v8, v9
	s_waitcnt vmcnt(23)
	global_store_dwordx4 v108, v[96:99], s[16:17]
	s_add_u32 s16, s16, 0x100000
	s_addc_u32 s17, s17, 0
	v_lshlrev_b32_e32 v100, 16, v22
	v_and_b32_e32 v101, 0xffff0000, v22
	v_lshlrev_b32_e32 v102, 16, v23
	v_and_b32_e32 v103, 0xffff0000, v23
	v_lshlrev_b32_e32 v104, 16, v24
	v_and_b32_e32 v105, 0xffff0000, v24
	v_lshlrev_b32_e32 v106, 16, v25
	v_and_b32_e32 v107, 0xffff0000, v25
	s_waitcnt lgkmcnt(2)
	v_pk_fma_f32 v[2:3], v[2:3], v[84:85], v[100:101]
	v_pk_fma_f32 v[4:5], v[4:5], v[86:87], v[102:103]
	v_pk_fma_f32 v[6:7], v[6:7], v[88:89], v[104:105]
	v_pk_fma_f32 v[8:9], v[8:9], v[90:91], v[106:107]
	ds_read_b128 v[84:87], v109 offset:54272
	ds_read_b128 v[88:91], v109 offset:54288
	v_cvt_pk_bf16_f32 v92, v2, v3
	v_cvt_pk_bf16_f32 v93, v4, v5
	v_cvt_pk_bf16_f32 v94, v6, v7
	v_cvt_pk_bf16_f32 v95, v8, v9
	s_waitcnt vmcnt(23)
	global_store_dwordx4 v108, v[92:95], s[16:17]
	s_add_u32 s16, s16, 0x100000
	s_addc_u32 s17, s17, 0
	v_lshlrev_b32_e32 v100, 16, v26
	v_and_b32_e32 v101, 0xffff0000, v26
	v_lshlrev_b32_e32 v102, 16, v27
	v_and_b32_e32 v103, 0xffff0000, v27
	v_lshlrev_b32_e32 v104, 16, v28
	v_and_b32_e32 v105, 0xffff0000, v28
	v_lshlrev_b32_e32 v106, 16, v29
	v_and_b32_e32 v107, 0xffff0000, v29
	s_waitcnt lgkmcnt(2)
	v_pk_fma_f32 v[2:3], v[2:3], v[76:77], v[100:101]
	v_pk_fma_f32 v[4:5], v[4:5], v[78:79], v[102:103]
	v_pk_fma_f32 v[6:7], v[6:7], v[80:81], v[104:105]
	v_pk_fma_f32 v[8:9], v[8:9], v[82:83], v[106:107]
	ds_read_b128 v[76:79], v109 offset:55296
	ds_read_b128 v[80:83], v109 offset:55312
	v_cvt_pk_bf16_f32 v96, v2, v3
	v_cvt_pk_bf16_f32 v97, v4, v5
	v_cvt_pk_bf16_f32 v98, v6, v7
	v_cvt_pk_bf16_f32 v99, v8, v9
	s_waitcnt vmcnt(23)
	global_store_dwordx4 v108, v[96:99], s[16:17]
	s_add_u32 s16, s16, 0x100000
	s_addc_u32 s17, s17, 0
	v_lshlrev_b32_e32 v100, 16, v30
	v_and_b32_e32 v101, 0xffff0000, v30
	v_lshlrev_b32_e32 v102, 16, v31
	v_and_b32_e32 v103, 0xffff0000, v31
	v_lshlrev_b32_e32 v104, 16, v32
	v_and_b32_e32 v105, 0xffff0000, v32
	v_lshlrev_b32_e32 v106, 16, v33
	v_and_b32_e32 v107, 0xffff0000, v33
	s_waitcnt lgkmcnt(2)
	v_pk_fma_f32 v[2:3], v[2:3], v[84:85], v[100:101]
	v_pk_fma_f32 v[4:5], v[4:5], v[86:87], v[102:103]
	v_pk_fma_f32 v[6:7], v[6:7], v[88:89], v[104:105]
	v_pk_fma_f32 v[8:9], v[8:9], v[90:91], v[106:107]
	ds_read_b128 v[84:87], v109 offset:56320
	ds_read_b128 v[88:91], v109 offset:56336
	v_cvt_pk_bf16_f32 v92, v2, v3
	v_cvt_pk_bf16_f32 v93, v4, v5
	v_cvt_pk_bf16_f32 v94, v6, v7
	v_cvt_pk_bf16_f32 v95, v8, v9
	s_waitcnt vmcnt(23)
	global_store_dwordx4 v108, v[92:95], s[16:17]
	s_add_u32 s16, s16, 0x100000
	s_addc_u32 s17, s17, 0
	v_lshlrev_b32_e32 v100, 16, v34
	v_and_b32_e32 v101, 0xffff0000, v34
	v_lshlrev_b32_e32 v102, 16, v35
	v_and_b32_e32 v103, 0xffff0000, v35
	v_lshlrev_b32_e32 v104, 16, v36
	v_and_b32_e32 v105, 0xffff0000, v36
	v_lshlrev_b32_e32 v106, 16, v37
	v_and_b32_e32 v107, 0xffff0000, v37
	s_waitcnt lgkmcnt(2)
	v_pk_fma_f32 v[2:3], v[2:3], v[76:77], v[100:101]
	v_pk_fma_f32 v[4:5], v[4:5], v[78:79], v[102:103]
	v_pk_fma_f32 v[6:7], v[6:7], v[80:81], v[104:105]
	v_pk_fma_f32 v[8:9], v[8:9], v[82:83], v[106:107]
	ds_read_b128 v[76:79], v109 offset:57344
	ds_read_b128 v[80:83], v109 offset:57360
	v_cvt_pk_bf16_f32 v96, v2, v3
	v_cvt_pk_bf16_f32 v97, v4, v5
	v_cvt_pk_bf16_f32 v98, v6, v7
	v_cvt_pk_bf16_f32 v99, v8, v9
	s_waitcnt vmcnt(23)
	global_store_dwordx4 v108, v[96:99], s[16:17]
	s_add_u32 s16, s16, 0x100000
	s_addc_u32 s17, s17, 0
	v_lshlrev_b32_e32 v100, 16, v38
	v_and_b32_e32 v101, 0xffff0000, v38
	v_lshlrev_b32_e32 v102, 16, v39
	v_and_b32_e32 v103, 0xffff0000, v39
	v_lshlrev_b32_e32 v104, 16, v40
	v_and_b32_e32 v105, 0xffff0000, v40
	v_lshlrev_b32_e32 v106, 16, v41
	v_and_b32_e32 v107, 0xffff0000, v41
	s_waitcnt lgkmcnt(2)
	v_pk_fma_f32 v[2:3], v[2:3], v[84:85], v[100:101]
	v_pk_fma_f32 v[4:5], v[4:5], v[86:87], v[102:103]
	v_pk_fma_f32 v[6:7], v[6:7], v[88:89], v[104:105]
	v_pk_fma_f32 v[8:9], v[8:9], v[90:91], v[106:107]
	ds_read_b128 v[84:87], v109 offset:58368
	ds_read_b128 v[88:91], v109 offset:58384
	v_cvt_pk_bf16_f32 v92, v2, v3
	v_cvt_pk_bf16_f32 v93, v4, v5
	v_cvt_pk_bf16_f32 v94, v6, v7
	v_cvt_pk_bf16_f32 v95, v8, v9
	s_waitcnt vmcnt(15)
	global_store_dwordx4 v108, v[92:95], s[16:17]
	s_add_u32 s16, s16, 0x100000
	s_addc_u32 s17, s17, 0
	v_lshlrev_b32_e32 v100, 16, v42
	v_and_b32_e32 v101, 0xffff0000, v42
	v_lshlrev_b32_e32 v102, 16, v43
	v_and_b32_e32 v103, 0xffff0000, v43
	v_lshlrev_b32_e32 v104, 16, v44
	v_and_b32_e32 v105, 0xffff0000, v44
	v_lshlrev_b32_e32 v106, 16, v45
	v_and_b32_e32 v107, 0xffff0000, v45
	s_waitcnt lgkmcnt(2)
	v_pk_fma_f32 v[2:3], v[2:3], v[76:77], v[100:101]
	v_pk_fma_f32 v[4:5], v[4:5], v[78:79], v[102:103]
	v_pk_fma_f32 v[6:7], v[6:7], v[80:81], v[104:105]
	v_pk_fma_f32 v[8:9], v[8:9], v[82:83], v[106:107]
	ds_read_b128 v[76:79], v109 offset:59392
	ds_read_b128 v[80:83], v109 offset:59408
	v_cvt_pk_bf16_f32 v96, v2, v3
	v_cvt_pk_bf16_f32 v97, v4, v5
	v_cvt_pk_bf16_f32 v98, v6, v7
	v_cvt_pk_bf16_f32 v99, v8, v9
	s_waitcnt vmcnt(15)
	global_store_dwordx4 v108, v[96:99], s[16:17]
	s_add_u32 s16, s16, 0x100000
	s_addc_u32 s17, s17, 0
	v_lshlrev_b32_e32 v100, 16, v46
	v_and_b32_e32 v101, 0xffff0000, v46
	v_lshlrev_b32_e32 v102, 16, v47
	v_and_b32_e32 v103, 0xffff0000, v47
	v_lshlrev_b32_e32 v104, 16, v48
	v_and_b32_e32 v105, 0xffff0000, v48
	v_lshlrev_b32_e32 v106, 16, v49
	v_and_b32_e32 v107, 0xffff0000, v49
	s_waitcnt lgkmcnt(2)
	v_pk_fma_f32 v[2:3], v[2:3], v[84:85], v[100:101]
	v_pk_fma_f32 v[4:5], v[4:5], v[86:87], v[102:103]
	v_pk_fma_f32 v[6:7], v[6:7], v[88:89], v[104:105]
	v_pk_fma_f32 v[8:9], v[8:9], v[90:91], v[106:107]
	ds_read_b128 v[84:87], v109 offset:60416
	ds_read_b128 v[88:91], v109 offset:60432
	v_cvt_pk_bf16_f32 v92, v2, v3
	v_cvt_pk_bf16_f32 v93, v4, v5
	v_cvt_pk_bf16_f32 v94, v6, v7
	v_cvt_pk_bf16_f32 v95, v8, v9
	s_waitcnt vmcnt(15)
	global_store_dwordx4 v108, v[92:95], s[16:17]
	s_add_u32 s16, s16, 0x100000
	s_addc_u32 s17, s17, 0
	v_lshlrev_b32_e32 v100, 16, v50
	v_and_b32_e32 v101, 0xffff0000, v50
	v_lshlrev_b32_e32 v102, 16, v51
	v_and_b32_e32 v103, 0xffff0000, v51
	v_lshlrev_b32_e32 v104, 16, v52
	v_and_b32_e32 v105, 0xffff0000, v52
	v_lshlrev_b32_e32 v106, 16, v53
	v_and_b32_e32 v107, 0xffff0000, v53
	s_waitcnt lgkmcnt(2)
	v_pk_fma_f32 v[2:3], v[2:3], v[76:77], v[100:101]
	v_pk_fma_f32 v[4:5], v[4:5], v[78:79], v[102:103]
	v_pk_fma_f32 v[6:7], v[6:7], v[80:81], v[104:105]
	v_pk_fma_f32 v[8:9], v[8:9], v[82:83], v[106:107]
	ds_read_b128 v[76:79], v109 offset:61440
	ds_read_b128 v[80:83], v109 offset:61456
	v_cvt_pk_bf16_f32 v96, v2, v3
	v_cvt_pk_bf16_f32 v97, v4, v5
	v_cvt_pk_bf16_f32 v98, v6, v7
	v_cvt_pk_bf16_f32 v99, v8, v9
	s_waitcnt vmcnt(15)
	global_store_dwordx4 v108, v[96:99], s[16:17]
	s_add_u32 s16, s16, 0x100000
	s_addc_u32 s17, s17, 0
	v_lshlrev_b32_e32 v100, 16, v54
	v_and_b32_e32 v101, 0xffff0000, v54
	v_lshlrev_b32_e32 v102, 16, v55
	v_and_b32_e32 v103, 0xffff0000, v55
	v_lshlrev_b32_e32 v104, 16, v56
	v_and_b32_e32 v105, 0xffff0000, v56
	v_lshlrev_b32_e32 v106, 16, v57
	v_and_b32_e32 v107, 0xffff0000, v57
	s_waitcnt lgkmcnt(2)
	v_pk_fma_f32 v[2:3], v[2:3], v[84:85], v[100:101]
	v_pk_fma_f32 v[4:5], v[4:5], v[86:87], v[102:103]
	v_pk_fma_f32 v[6:7], v[6:7], v[88:89], v[104:105]
	v_pk_fma_f32 v[8:9], v[8:9], v[90:91], v[106:107]
	ds_read_b128 v[84:87], v109 offset:62464
	ds_read_b128 v[88:91], v109 offset:62480
	v_cvt_pk_bf16_f32 v92, v2, v3
	v_cvt_pk_bf16_f32 v93, v4, v5
	v_cvt_pk_bf16_f32 v94, v6, v7
	v_cvt_pk_bf16_f32 v95, v8, v9
	s_waitcnt vmcnt(15)
	global_store_dwordx4 v108, v[92:95], s[16:17]
	s_add_u32 s16, s16, 0x100000
	s_addc_u32 s17, s17, 0
	v_lshlrev_b32_e32 v100, 16, v58
	v_and_b32_e32 v101, 0xffff0000, v58
	v_lshlrev_b32_e32 v102, 16, v59
	v_and_b32_e32 v103, 0xffff0000, v59
	v_lshlrev_b32_e32 v104, 16, v60
	v_and_b32_e32 v105, 0xffff0000, v60
	v_lshlrev_b32_e32 v106, 16, v61
	v_and_b32_e32 v107, 0xffff0000, v61
	s_waitcnt lgkmcnt(2)
	v_pk_fma_f32 v[2:3], v[2:3], v[76:77], v[100:101]
	v_pk_fma_f32 v[4:5], v[4:5], v[78:79], v[102:103]
	v_pk_fma_f32 v[6:7], v[6:7], v[80:81], v[104:105]
	v_pk_fma_f32 v[8:9], v[8:9], v[82:83], v[106:107]
	ds_read_b128 v[76:79], v109 offset:63488
	ds_read_b128 v[80:83], v109 offset:63504
	v_cvt_pk_bf16_f32 v96, v2, v3
	v_cvt_pk_bf16_f32 v97, v4, v5
	v_cvt_pk_bf16_f32 v98, v6, v7
	v_cvt_pk_bf16_f32 v99, v8, v9
	s_waitcnt vmcnt(15)
	global_store_dwordx4 v108, v[96:99], s[16:17]
	s_add_u32 s16, s16, 0x100000
	s_addc_u32 s17, s17, 0
	v_lshlrev_b32_e32 v100, 16, v62
	v_and_b32_e32 v101, 0xffff0000, v62
	v_lshlrev_b32_e32 v102, 16, v63
	v_and_b32_e32 v103, 0xffff0000, v63
	v_lshlrev_b32_e32 v104, 16, v64
	v_and_b32_e32 v105, 0xffff0000, v64
	v_lshlrev_b32_e32 v106, 16, v65
	v_and_b32_e32 v107, 0xffff0000, v65
	s_waitcnt lgkmcnt(2)
	v_pk_fma_f32 v[2:3], v[2:3], v[84:85], v[100:101]
	v_pk_fma_f32 v[4:5], v[4:5], v[86:87], v[102:103]
	v_pk_fma_f32 v[6:7], v[6:7], v[88:89], v[104:105]
	v_pk_fma_f32 v[8:9], v[8:9], v[90:91], v[106:107]
	ds_read_b128 v[84:87], v109 offset:64512
	ds_read_b128 v[88:91], v109 offset:64528
	v_cvt_pk_bf16_f32 v92, v2, v3
	v_cvt_pk_bf16_f32 v93, v4, v5
	v_cvt_pk_bf16_f32 v94, v6, v7
	v_cvt_pk_bf16_f32 v95, v8, v9
	s_waitcnt vmcnt(15)
	global_store_dwordx4 v108, v[92:95], s[16:17]
	s_add_u32 s16, s16, 0x100000
	s_addc_u32 s17, s17, 0
	v_lshlrev_b32_e32 v100, 16, v68
	v_and_b32_e32 v101, 0xffff0000, v68
	v_lshlrev_b32_e32 v102, 16, v69
	v_and_b32_e32 v103, 0xffff0000, v69
	v_lshlrev_b32_e32 v104, 16, v70
	v_and_b32_e32 v105, 0xffff0000, v70
	v_lshlrev_b32_e32 v106, 16, v71
	v_and_b32_e32 v107, 0xffff0000, v71
	s_waitcnt lgkmcnt(2)
	v_pk_fma_f32 v[2:3], v[2:3], v[76:77], v[100:101]
	v_pk_fma_f32 v[4:5], v[4:5], v[78:79], v[102:103]
	v_pk_fma_f32 v[6:7], v[6:7], v[80:81], v[104:105]
	v_pk_fma_f32 v[8:9], v[8:9], v[82:83], v[106:107]
	v_cvt_pk_bf16_f32 v96, v2, v3
	v_cvt_pk_bf16_f32 v97, v4, v5
	v_cvt_pk_bf16_f32 v98, v6, v7
	v_cvt_pk_bf16_f32 v99, v8, v9
	s_waitcnt vmcnt(15)
	global_store_dwordx4 v108, v[96:99], s[16:17]
	s_add_u32 s16, s16, 0x100000
	s_addc_u32 s17, s17, 0
	v_lshlrev_b32_e32 v100, 16, v72
	v_and_b32_e32 v101, 0xffff0000, v72
	v_lshlrev_b32_e32 v102, 16, v73
	v_and_b32_e32 v103, 0xffff0000, v73
	v_lshlrev_b32_e32 v104, 16, v74
	v_and_b32_e32 v105, 0xffff0000, v74
	v_lshlrev_b32_e32 v106, 16, v75
	v_and_b32_e32 v107, 0xffff0000, v75
	s_waitcnt lgkmcnt(0)
	v_pk_fma_f32 v[2:3], v[2:3], v[84:85], v[100:101]
	v_pk_fma_f32 v[4:5], v[4:5], v[86:87], v[102:103]
	v_pk_fma_f32 v[6:7], v[6:7], v[88:89], v[104:105]
	v_pk_fma_f32 v[8:9], v[8:9], v[90:91], v[106:107]

.Lscan16_orig:
	s_add_u32 s12, s4, 0x50000000
	s_addc_u32 s13, s2, 0
	s_add_u32 s14, s4, 0x4ff00000
	s_addc_u32 s15, s2, 0
	s_mov_b64 s[16:17], 0
	s_waitcnt vmcnt(4)
	v_mov_b64_e32 v[70:71], v[66:67]

.LBB0_783:
	s_or_b64 exec, exec, s[64:65]
	s_waitcnt vmcnt(4)
	v_pk_mul_f32 v[160:161], v[160:161], s[34:35] op_sel_hi:[1,0]
	v_pk_mul_f32 v[158:159], v[158:159], s[34:35] op_sel_hi:[1,0]
	v_pk_mul_f32 v[148:149], v[148:149], s[34:35] op_sel_hi:[1,0]
	v_pk_mul_f32 v[146:147], v[146:147], s[34:35] op_sel_hi:[1,0]
	v_pk_mul_f32 v[156:157], v[156:157], s[34:35] op_sel_hi:[1,0]
	v_pk_mul_f32 v[154:155], v[154:155], s[34:35] op_sel_hi:[1,0]
	v_pk_fma_f32 v[162:163], v[160:161], v[204:205], v[148:149]
	v_pk_fma_f32 v[164:165], v[158:159], v[202:203], v[146:147]
	v_pk_mul_f32 v[152:153], v[152:153], s[34:35] op_sel_hi:[1,0]
	v_pk_mul_f32 v[150:151], v[150:151], s[34:35] op_sel_hi:[1,0]
	v_pk_fma_f32 v[164:165], v[154:155], v[198:199], v[164:165]
	v_pk_fma_f32 v[162:163], v[156:157], v[200:201], v[162:163]
	v_pk_fma_f32 v[166:167], v[160:161], v[200:201], v[148:149]
	v_pk_fma_f32 v[170:171], v[158:159], v[198:199], v[146:147]
	v_pk_fma_f32 v[162:163], v[128:129], v[152:153], v[162:163]
	v_pk_fma_f32 v[164:165], v[126:127], v[150:151], v[164:165]
	v_pk_fma_f32 v[170:171], v[126:127], v[154:155], v[170:171]
	v_pk_fma_f32 v[166:167], v[128:129], v[156:157], v[166:167]
	v_pk_fma_f32 v[128:129], v[128:129], v[160:161], v[148:149]
	v_pk_fma_f32 v[126:127], v[126:127], v[158:159], v[146:147]
	v_pk_fma_f32 v[166:167], v[124:125], v[152:153], v[166:167]
	v_pk_fma_f32 v[170:171], v[122:123], v[150:151], v[170:171]
	v_pk_fma_f32 v[126:127], v[122:123], v[154:155], v[126:127]
	v_pk_fma_f32 v[128:129], v[124:125], v[156:157], v[128:129]
	v_pk_fma_f32 v[124:125], v[124:125], v[160:161], v[148:149]
	v_pk_fma_f32 v[122:123], v[122:123], v[158:159], v[146:147]
	v_pk_fma_f32 v[128:129], v[120:121], v[152:153], v[128:129]
	v_pk_fma_f32 v[126:127], v[118:119], v[150:151], v[126:127]
	v_pk_fma_f32 v[118:119], v[118:119], v[154:155], v[122:123]
	v_pk_fma_f32 v[120:121], v[120:121], v[156:157], v[124:125]
	v_exp_f32_e64 v122, -v164
	v_exp_f32_e64 v124, -v162
	v_exp_f32_e64 v125, -v163
	v_exp_f32_e64 v123, -v165
	v_pk_fma_f32 v[120:121], v[116:117], v[152:153], v[120:121]
	v_pk_fma_f32 v[118:119], v[114:115], v[150:151], v[118:119]
	v_pk_fma_f32 v[114:115], v[124:125], s[34:35], s[34:35] op_sel_hi:[1,0,0]
	v_pk_fma_f32 v[116:117], v[122:123], s[34:35], s[34:35] op_sel_hi:[1,0,0]
	v_rcp_f32_e32 v114, v114
	v_rcp_f32_e32 v116, v116
	v_rcp_f32_e32 v117, v117
	v_rcp_f32_e32 v115, v115
	v_exp_f32_e64 v122, -v170
	v_exp_f32_e64 v124, -v166
	v_exp_f32_e64 v125, -v167
	v_exp_f32_e64 v123, -v171
	v_pk_mul_f32 v[110:111], v[110:111], v[164:165]
	v_pk_mul_f32 v[112:113], v[112:113], v[162:163]
	v_pk_mul_f32 v[116:117], v[110:111], v[116:117]
	v_pk_mul_f32 v[114:115], v[112:113], v[114:115]
	v_pk_fma_f32 v[110:111], v[124:125], s[34:35], s[34:35] op_sel_hi:[1,0,0]
	v_pk_fma_f32 v[112:113], v[122:123], s[34:35], s[34:35] op_sel_hi:[1,0,0]
	v_rcp_f32_e32 v110, v110
	v_rcp_f32_e32 v112, v112
	v_rcp_f32_e32 v113, v113
	v_rcp_f32_e32 v111, v111
	v_exp_f32_e64 v122, -v126
	v_exp_f32_e64 v124, -v128
	v_exp_f32_e64 v125, -v129
	v_exp_f32_e64 v123, -v127
	v_pk_mul_f32 v[106:107], v[106:107], v[170:171]
	v_pk_mul_f32 v[108:109], v[108:109], v[166:167]
	v_pk_mul_f32 v[164:165], v[106:107], v[112:113]
	v_pk_mul_f32 v[162:163], v[108:109], v[110:111]
	v_pk_fma_f32 v[106:107], v[124:125], s[34:35], s[34:35] op_sel_hi:[1,0,0]
	v_pk_fma_f32 v[108:109], v[122:123], s[34:35], s[34:35] op_sel_hi:[1,0,0]
	v_rcp_f32_e32 v106, v106
	v_rcp_f32_e32 v108, v108
	v_rcp_f32_e32 v109, v109
	v_rcp_f32_e32 v107, v107
	v_exp_f32_e64 v110, -v118
	v_exp_f32_e64 v112, -v120
	v_exp_f32_e64 v113, -v121
	v_exp_f32_e64 v111, -v119
	v_pk_mul_f32 v[102:103], v[102:103], v[126:127]
	v_pk_mul_f32 v[104:105], v[104:105], v[128:129]
	v_pk_mul_f32 v[124:125], v[102:103], v[108:109]
	v_pk_mul_f32 v[122:123], v[104:105], v[106:107]
	v_pk_fma_f32 v[102:103], v[112:113], s[34:35], s[34:35] op_sel_hi:[1,0,0]
	v_pk_fma_f32 v[104:105], v[110:111], s[34:35], s[34:35] op_sel_hi:[1,0,0]
	v_rcp_f32_e32 v102, v102
	v_rcp_f32_e32 v104, v104
	v_rcp_f32_e32 v103, v103
	v_rcp_f32_e32 v105, v105
	v_pk_mul_f32 v[98:99], v[98:99], v[118:119]
	v_pk_mul_f32 v[100:101], v[100:101], v[120:121]
	v_pk_mul_f32 v[112:113], v[132:133], s[34:35] op_sel_hi:[1,0]
	v_pk_mul_f32 v[118:119], v[100:101], v[102:103]
	v_pk_mul_f32 v[120:121], v[98:99], v[104:105]
	v_pk_mul_f32 v[100:101], v[144:145], s[34:35] op_sel_hi:[1,0]
	v_pk_mul_f32 v[98:99], v[142:143], s[34:35] op_sel_hi:[1,0]
	v_pk_mul_f32 v[110:111], v[130:131], s[34:35] op_sel_hi:[1,0]
	v_pk_mul_f32 v[104:105], v[140:141], s[34:35] op_sel_hi:[1,0]
	v_pk_mul_f32 v[102:103], v[138:139], s[34:35] op_sel_hi:[1,0]
	v_pk_fma_f32 v[126:127], v[100:101], v[196:197], v[112:113]
	v_pk_fma_f32 v[128:129], v[98:99], v[194:195], v[110:111]
	v_pk_mul_f32 v[108:109], v[136:137], s[34:35] op_sel_hi:[1,0]
	v_pk_mul_f32 v[106:107], v[134:135], s[34:35] op_sel_hi:[1,0]
	v_pk_fma_f32 v[128:129], v[102:103], v[190:191], v[128:129]
	v_pk_fma_f32 v[126:127], v[104:105], v[192:193], v[126:127]
	v_pk_fma_f32 v[130:131], v[100:101], v[192:193], v[112:113]
	v_pk_fma_f32 v[132:133], v[98:99], v[190:191], v[110:111]
	v_pk_fma_f32 v[126:127], v[96:97], v[108:109], v[126:127]
	v_pk_fma_f32 v[128:129], v[94:95], v[106:107], v[128:129]
	v_pk_fma_f32 v[132:133], v[94:95], v[102:103], v[132:133]
	v_pk_fma_f32 v[130:131], v[96:97], v[104:105], v[130:131]
	v_pk_fma_f32 v[96:97], v[96:97], v[100:101], v[112:113]
	v_pk_fma_f32 v[94:95], v[94:95], v[98:99], v[110:111]
	v_pk_fma_f32 v[130:131], v[92:93], v[108:109], v[130:131]
	v_pk_fma_f32 v[132:133], v[90:91], v[106:107], v[132:133]
	v_pk_fma_f32 v[96:97], v[92:93], v[104:105], v[96:97]
	v_pk_fma_f32 v[94:95], v[90:91], v[102:103], v[94:95]
	v_pk_fma_f32 v[92:93], v[92:93], v[100:101], v[112:113]
	v_pk_fma_f32 v[90:91], v[90:91], v[98:99], v[110:111]
	v_pk_fma_f32 v[96:97], v[88:89], v[108:109], v[96:97]
	v_pk_fma_f32 v[94:95], v[86:87], v[106:107], v[94:95]
	v_pk_fma_f32 v[88:89], v[88:89], v[104:105], v[92:93]
	v_pk_fma_f32 v[86:87], v[86:87], v[102:103], v[90:91]
	v_exp_f32_e64 v90, -v128
	v_exp_f32_e64 v92, -v126
	v_exp_f32_e64 v93, -v127
	v_exp_f32_e64 v91, -v129
	v_pk_fma_f32 v[84:85], v[84:85], v[108:109], v[88:89]
	v_pk_fma_f32 v[82:83], v[82:83], v[106:107], v[86:87]
	v_pk_fma_f32 v[86:87], v[92:93], s[34:35], s[34:35] op_sel_hi:[1,0,0]
	v_pk_fma_f32 v[88:89], v[90:91], s[34:35], s[34:35] op_sel_hi:[1,0,0]
	v_rcp_f32_e32 v86, v86
	v_rcp_f32_e32 v88, v88
	v_rcp_f32_e32 v89, v89
	v_rcp_f32_e32 v87, v87
	v_exp_f32_e64 v90, -v132
	v_exp_f32_e64 v92, -v130
	v_exp_f32_e64 v93, -v131
	v_exp_f32_e64 v91, -v133
	v_pk_mul_f32 v[78:79], v[78:79], v[128:129]
	v_pk_mul_f32 v[80:81], v[80:81], v[126:127]
	v_pk_mul_f32 v[78:79], v[78:79], v[88:89]
	v_pk_mul_f32 v[80:81], v[80:81], v[86:87]
	v_pk_fma_f32 v[86:87], v[92:93], s[34:35], s[34:35] op_sel_hi:[1,0,0]
	v_pk_fma_f32 v[88:89], v[90:91], s[34:35], s[34:35] op_sel_hi:[1,0,0]
	v_rcp_f32_e32 v86, v86
	v_rcp_f32_e32 v88, v88
	v_rcp_f32_e32 v89, v89
	v_rcp_f32_e32 v87, v87
	v_exp_f32_e64 v90, -v94
	v_exp_f32_e64 v92, -v96
	v_exp_f32_e64 v93, -v97
	v_exp_f32_e64 v91, -v95
	v_pk_mul_f32 v[74:75], v[74:75], v[132:133]
	v_pk_mul_f32 v[76:77], v[76:77], v[130:131]
	v_pk_mul_f32 v[74:75], v[74:75], v[88:89]
	v_pk_mul_f32 v[76:77], v[76:77], v[86:87]
	v_pk_fma_f32 v[86:87], v[92:93], s[34:35], s[34:35] op_sel_hi:[1,0,0]
	v_pk_fma_f32 v[88:89], v[90:91], s[34:35], s[34:35] op_sel_hi:[1,0,0]
	v_rcp_f32_e32 v86, v86
	v_rcp_f32_e32 v88, v88
	v_rcp_f32_e32 v89, v89
	v_rcp_f32_e32 v87, v87
	v_exp_f32_e64 v90, -v82
	v_exp_f32_e64 v91, -v83
	v_exp_f32_e64 v92, -v84
	v_exp_f32_e64 v93, -v85
	v_pk_mul_f32 v[72:73], v[72:73], v[96:97]
	v_pk_mul_f32 v[70:71], v[70:71], v[94:95]
	v_pk_mul_f32 v[72:73], v[72:73], v[86:87]
	v_pk_mul_f32 v[86:87], v[70:71], v[88:89]
	v_pk_fma_f32 v[88:89], v[90:91], s[34:35], s[34:35] op_sel_hi:[1,0,0]
	v_pk_fma_f32 v[70:71], v[92:93], s[34:35], s[34:35] op_sel_hi:[1,0,0]
	v_rcp_f32_e32 v88, v88
	v_rcp_f32_e32 v89, v89
	v_rcp_f32_e32 v70, v70
	v_rcp_f32_e32 v71, v71
	v_pk_mul_f32 v[66:67], v[66:67], v[82:83]
	v_pk_mul_f32 v[68:69], v[68:69], v[84:85]
	v_pk_mul_f32 v[84:85], v[66:67], v[88:89]
	v_or_b32_e32 v88, s49, v219
	v_cvt_pk_bf16_f32 v66, v78, v79
	v_mov_b64_e32 v[78:79], s[16:17]
	s_movk_i32 s51, 0x2c00
	v_pk_mul_f32 v[82:83], v[68:69], v[70:71]
	v_cvt_pk_bf16_f32 v67, v80, v81
	v_mad_i64_i32 v[80:81], s[30:31], v88, s51, v[78:79]
	v_lshlrev_b64 v[70:71], 1, v[188:189]
	v_cvt_pk_bf16_f32 v68, v116, v117
	v_cvt_pk_bf16_f32 v69, v114, v115
	v_lshl_add_u64 v[80:81], v[80:81], 0, v[70:71]
	global_store_dwordx4 v[80:81], v[66:69], off
	v_cmp_lt_i32_e32 vcc, 14, v218
	s_mov_b64 s[62:63], 0
	v_cvt_pk_bf16_f32 v66, v74, v75
	v_or_b32_e32 v74, 1, v88
	v_mad_i64_i32 v[74:75], s[30:31], v74, s51, v[78:79]
	v_cvt_pk_bf16_f32 v67, v76, v77
	v_cvt_pk_bf16_f32 v68, v164, v165
	v_cvt_pk_bf16_f32 v69, v162, v163
	v_lshl_add_u64 v[74:75], v[74:75], 0, v[70:71]
	global_store_dwordx4 v[74:75], v[66:69], off
	v_mov_b32_e32 v74, v1
	v_mov_b32_e32 v75, v1
	v_cvt_pk_bf16_f32 v67, v72, v73
	v_or_b32_e32 v72, 2, v88
	v_mad_i64_i32 v[72:73], s[30:31], v72, s51, v[78:79]
	v_cvt_pk_bf16_f32 v66, v86, v87
	v_cvt_pk_bf16_f32 v68, v124, v125
	v_cvt_pk_bf16_f32 v69, v122, v123
	v_lshl_add_u64 v[72:73], v[72:73], 0, v[70:71]
	global_store_dwordx4 v[72:73], v[66:69], off
	v_or_b32_e32 v72, 3, v88
	v_mad_i64_i32 v[72:73], s[30:31], v72, s51, v[78:79]
	v_cvt_pk_bf16_f32 v66, v84, v85
	v_cvt_pk_bf16_f32 v67, v82, v83
	v_cvt_pk_bf16_f32 v68, v120, v121
	v_cvt_pk_bf16_f32 v69, v118, v119
	v_lshl_add_u64 v[72:73], v[72:73], 0, v[70:71]
	global_store_dwordx4 v[72:73], v[66:69], off
	v_mov_b32_e32 v72, v1
	v_mov_b32_e32 v73, v1
	v_mov_b32_e32 v76, v1
	v_mov_b32_e32 v78, v1
	v_mov_b32_e32 v77, v1
	v_mov_b32_e32 v79, v1
	v_mov_b32_dpp v72, v30 row_shr:1 row_mask:0xf bank_mask:0xf
	v_mov_b32_dpp v74, v26 row_shr:1 row_mask:0xf bank_mask:0xf
	v_mov_b32_dpp v73, v31 row_shr:1 row_mask:0xf bank_mask:0xf
	v_mov_b32_dpp v75, v27 row_shr:1 row_mask:0xf bank_mask:0xf
	v_mov_b32_dpp v76, v32 row_shr:1 row_mask:0xf bank_mask:0xf
	v_mov_b32_dpp v78, v28 row_shr:1 row_mask:0xf bank_mask:0xf
	v_mov_b32_dpp v77, v33 row_shr:1 row_mask:0xf bank_mask:0xf
	v_mov_b32_dpp v79, v29 row_shr:1 row_mask:0xf bank_mask:0xf
	s_and_saveexec_b64 s[30:31], vcc
	s_xor_b64 s[64:65], exec, s[30:31]
	s_mov_b64 s[62:63], exec
	v_cvt_pk_bf16_f32 v66, v26, v27
	v_cvt_pk_bf16_f32 v67, v28, v29
	v_cvt_pk_bf16_f32 v68, v30, v31
	v_cvt_pk_bf16_f32 v69, v32, v33
	s_or_saveexec_b64 s[64:65], s[64:65]
	s_addk_i32 s49, 0x80
	s_ashr_i32 s30, s49, 6
	v_mad_i64_i32 v[80:81], s[72:73], s30, v235, v[184:185]
	v_lshlrev_b64 v[80:81], 4, v[80:81]
	v_mov_b64_e32 v[82:83], 0x72c00000
	s_xor_b64 exec, exec, s[64:65]
	s_cbranch_execz .LBB0_789
	v_cmp_eq_u32_e32 vcc, 0, v218
	s_mov_b64 s[74:75], s[62:63]
	s_and_saveexec_b64 s[72:73], vcc
	s_cbranch_execz .LBB0_788
	v_cvt_pk_bf16_f32 v82, v10, v11
	v_cvt_pk_bf16_f32 v83, v12, v13
	v_cvt_pk_bf16_f32 v84, v18, v19
	v_cvt_pk_bf16_f32 v85, v20, v21
	v_cvt_pk_bf16_f32 v66, v2, v3
	v_cvt_pk_bf16_f32 v67, v4, v5
	v_cvt_pk_bf16_f32 v68, v6, v7
	v_cvt_pk_bf16_f32 v69, v8, v9
	v_lshl_add_u64 v[86:87], s[40:41], 0, v[80:81]
	s_or_b64 s[74:75], s[62:63], exec
	global_store_dwordx4 v[86:87], v[82:85], off
